# v66 + head of every MFMA phase shortened in the 6 large K-loops: redundant s_waitcnt lgkmcnt(0) after the barrier dropped, s_setprio 1 issued before the barrier
# speedup vs baseline: 1.0120x; 1.0049x over previous
.LBB0_162:
	ds_read_b128 v[154:157], v151
	ds_read_b128 v[158:161], v151 offset:1024
	ds_read_b128 v[162:165], v151 offset:2048
	ds_read_b128 v[166:169], v151 offset:3072
	ds_read_b128 v[170:173], v152
	ds_read_b128 v[174:177], v152 offset:1024
	ds_read_b128 v[178:181], v152 offset:2048
	ds_read_b128 v[182:185], v152 offset:3072
	s_add_u32 s58, s40, 0xfff00080
	s_addc_u32 s59, s41, -1
	s_cmp_eq_u32 s73, 60
	s_cselect_b32 s63, s25, s59
	s_cselect_b32 s62, s67, s58
	s_cselect_b32 s59, s23, s72
	s_cselect_b32 s58, s70, s71
	v_lshl_add_u64 v[146:147], s[40:41], 0, v[138:139]
	s_add_i32 m0, s42, 0xc000
	ds_read_b128 v[186:189], v153
	ds_read_b128 v[190:193], v153 offset:1024
	ds_read_b128 v[194:197], v153 offset:2048
	ds_read_b128 v[198:201], v153 offset:3072
	ds_read_b128 v[202:205], v153 offset:4096
	ds_read_b128 v[206:209], v153 offset:5120
	ds_read_b128 v[210:213], v153 offset:6144
	ds_read_b128 v[214:217], v153 offset:7168
	global_load_lds_dwordx4 v[146:147], off
	v_lshl_add_u64 v[146:147], s[40:41], 0, v[140:141]
	s_add_i32 m0, s42, 0xe000
	s_nop 0
	global_load_lds_dwordx4 v[146:147], off
	s_waitcnt vmcnt(8)
	s_waitcnt lgkmcnt(0)
	s_setprio 1
	s_barrier
	v_mfma_f32_16x16x32_bf16 v[126:129], v[154:157], v[186:189], v[126:129]
	v_mfma_f32_16x16x32_bf16 v[118:121], v[162:165], v[186:189], v[118:121]
	v_mfma_f32_16x16x32_bf16 v[110:113], v[154:157], v[194:197], v[110:113]
	v_mfma_f32_16x16x32_bf16 v[102:105], v[162:165], v[194:197], v[102:105]
	v_mfma_f32_16x16x32_bf16 v[94:97], v[154:157], v[202:205], v[94:97]
	v_mfma_f32_16x16x32_bf16 v[86:89], v[162:165], v[202:205], v[86:89]
	v_mfma_f32_16x16x32_bf16 v[78:81], v[154:157], v[210:213], v[78:81]
	v_mfma_f32_16x16x32_bf16 v[70:73], v[162:165], v[210:213], v[70:73]
	v_mfma_f32_16x16x32_bf16 v[126:129], v[158:161], v[190:193], v[126:129]
	v_mfma_f32_16x16x32_bf16 v[118:121], v[166:169], v[190:193], v[118:121]
	v_mfma_f32_16x16x32_bf16 v[110:113], v[158:161], v[198:201], v[110:113]
	v_mfma_f32_16x16x32_bf16 v[102:105], v[166:169], v[198:201], v[102:105]
	v_mfma_f32_16x16x32_bf16 v[94:97], v[158:161], v[206:209], v[94:97]
	v_mfma_f32_16x16x32_bf16 v[86:89], v[166:169], v[206:209], v[86:89]
	v_mfma_f32_16x16x32_bf16 v[78:81], v[158:161], v[214:217], v[78:81]
	v_mfma_f32_16x16x32_bf16 v[70:73], v[166:169], v[214:217], v[70:73]
	s_setprio 0
	s_setprio 1
	v_mfma_f32_16x16x32_bf16 v[122:125], v[170:173], v[186:189], v[122:125]
	v_mfma_f32_16x16x32_bf16 v[114:117], v[178:181], v[186:189], v[114:117]
	v_mfma_f32_16x16x32_bf16 v[106:109], v[170:173], v[194:197], v[106:109]
	v_mfma_f32_16x16x32_bf16 v[98:101], v[178:181], v[194:197], v[98:101]
	v_mfma_f32_16x16x32_bf16 v[90:93], v[170:173], v[202:205], v[90:93]
	v_mfma_f32_16x16x32_bf16 v[82:85], v[178:181], v[202:205], v[82:85]
	v_mfma_f32_16x16x32_bf16 v[74:77], v[170:173], v[210:213], v[74:77]
	v_mfma_f32_16x16x32_bf16 v[66:69], v[178:181], v[210:213], v[66:69]
	v_mfma_f32_16x16x32_bf16 v[122:125], v[174:177], v[190:193], v[122:125]
	v_mfma_f32_16x16x32_bf16 v[114:117], v[182:185], v[190:193], v[114:117]
	v_mfma_f32_16x16x32_bf16 v[106:109], v[174:177], v[198:201], v[106:109]
	v_mfma_f32_16x16x32_bf16 v[98:101], v[182:185], v[198:201], v[98:101]
	v_mfma_f32_16x16x32_bf16 v[90:93], v[174:177], v[206:209], v[90:93]
	v_mfma_f32_16x16x32_bf16 v[82:85], v[182:185], v[206:209], v[82:85]
	v_mfma_f32_16x16x32_bf16 v[74:77], v[174:177], v[214:217], v[74:77]
	v_mfma_f32_16x16x32_bf16 v[66:69], v[182:185], v[214:217], v[66:69]
	s_setprio 0
	s_barrier
	s_add_i32 s74, s50, s15
	v_lshl_add_u64 v[146:147], s[58:59], 0, v[134:135]
	s_mov_b32 m0, s74
	ds_read_b128 v[186:189], v153 offset:16384
	ds_read_b128 v[190:193], v153 offset:17408
	ds_read_b128 v[194:197], v153 offset:18432
	ds_read_b128 v[198:201], v153 offset:19456
	ds_read_b128 v[202:205], v153 offset:20480
	ds_read_b128 v[206:209], v153 offset:21504
	ds_read_b128 v[210:213], v153 offset:22528
	ds_read_b128 v[214:217], v153 offset:23552
	global_load_lds_dwordx4 v[146:147], off
	s_add_i32 m0, s74, 0x2000
	s_add_u32 s74, s58, 0x100000
	v_lshl_add_u64 v[218:219], s[58:59], 0, v[130:131]
	s_addc_u32 s75, s59, 0
	s_add_i32 s82, s51, s15
	global_load_lds_dwordx4 v[218:219], off
	v_lshl_add_u64 v[220:221], s[74:75], 0, v[134:135]
	s_mov_b32 m0, s82
	v_lshl_add_u64 v[222:223], s[62:63], 0, v[132:133]
	global_load_lds_dwordx4 v[220:221], off
	v_lshl_add_u64 v[220:221], s[74:75], 0, v[130:131]
	s_add_i32 m0, s82, 0x2000
	s_nop 0
	global_load_lds_dwordx4 v[220:221], off
	v_lshl_add_u64 v[220:221], s[62:63], 0, v[136:137]
	s_mov_b32 m0, s42
	s_nop 0
	global_load_lds_dwordx4 v[220:221], off
	s_mov_b32 m0, s43
	s_nop 0
	global_load_lds_dwordx4 v[222:223], off
	s_waitcnt vmcnt(8)
	s_waitcnt lgkmcnt(0)
	s_setprio 1
	s_barrier
	v_mfma_f32_16x16x32_bf16 v[62:65], v[154:157], v[186:189], v[62:65]
	v_mfma_f32_16x16x32_bf16 v[54:57], v[162:165], v[186:189], v[54:57]
	v_mfma_f32_16x16x32_bf16 v[46:49], v[154:157], v[194:197], v[46:49]
	v_mfma_f32_16x16x32_bf16 v[38:41], v[162:165], v[194:197], v[38:41]
	v_mfma_f32_16x16x32_bf16 v[30:33], v[154:157], v[202:205], v[30:33]
	v_mfma_f32_16x16x32_bf16 v[22:25], v[162:165], v[202:205], v[22:25]
	v_mfma_f32_16x16x32_bf16 v[14:17], v[154:157], v[210:213], v[14:17]
	v_mfma_f32_16x16x32_bf16 v[6:9], v[162:165], v[210:213], v[6:9]
	v_mfma_f32_16x16x32_bf16 v[62:65], v[158:161], v[190:193], v[62:65]
	v_mfma_f32_16x16x32_bf16 v[54:57], v[166:169], v[190:193], v[54:57]
	v_mfma_f32_16x16x32_bf16 v[46:49], v[158:161], v[198:201], v[46:49]
	v_mfma_f32_16x16x32_bf16 v[38:41], v[166:169], v[198:201], v[38:41]
	v_mfma_f32_16x16x32_bf16 v[30:33], v[158:161], v[206:209], v[30:33]
	v_mfma_f32_16x16x32_bf16 v[22:25], v[166:169], v[206:209], v[22:25]
	v_mfma_f32_16x16x32_bf16 v[14:17], v[158:161], v[214:217], v[14:17]
	v_mfma_f32_16x16x32_bf16 v[6:9], v[166:169], v[214:217], v[6:9]
	s_setprio 0
	s_setprio 1
	v_mfma_f32_16x16x32_bf16 v[58:61], v[170:173], v[186:189], v[58:61]
	v_mfma_f32_16x16x32_bf16 v[50:53], v[178:181], v[186:189], v[50:53]
	v_mfma_f32_16x16x32_bf16 v[42:45], v[170:173], v[194:197], v[42:45]
	v_mfma_f32_16x16x32_bf16 v[34:37], v[178:181], v[194:197], v[34:37]
	v_mfma_f32_16x16x32_bf16 v[26:29], v[170:173], v[202:205], v[26:29]
	v_mfma_f32_16x16x32_bf16 v[18:21], v[178:181], v[202:205], v[18:21]
	v_mfma_f32_16x16x32_bf16 v[10:13], v[170:173], v[210:213], v[10:13]
	v_mfma_f32_16x16x32_bf16 v[2:5], v[178:181], v[210:213], v[2:5]
	v_mfma_f32_16x16x32_bf16 v[58:61], v[174:177], v[190:193], v[58:61]
	v_mfma_f32_16x16x32_bf16 v[50:53], v[182:185], v[190:193], v[50:53]
	v_mfma_f32_16x16x32_bf16 v[42:45], v[174:177], v[198:201], v[42:45]
	v_mfma_f32_16x16x32_bf16 v[34:37], v[182:185], v[198:201], v[34:37]
	v_mfma_f32_16x16x32_bf16 v[26:29], v[174:177], v[206:209], v[26:29]
	v_mfma_f32_16x16x32_bf16 v[18:21], v[182:185], v[206:209], v[18:21]
	v_mfma_f32_16x16x32_bf16 v[10:13], v[174:177], v[214:217], v[10:13]
	v_mfma_f32_16x16x32_bf16 v[2:5], v[182:185], v[214:217], v[2:5]
	s_setprio 0
	s_barrier
	s_add_i32 s74, 0, 0x18000
	s_add_i32 s75, 0, 0x1c000
	v_add_u32_e32 v166, s74, v149
	v_add_u32_e32 v182, s75, v149
	ds_read_b128 v[154:157], v166
	ds_read_b128 v[158:161], v166 offset:1024
	ds_read_b128 v[162:165], v166 offset:2048
	ds_read_b128 v[166:169], v166 offset:3072
	ds_read_b128 v[170:173], v182
	ds_read_b128 v[174:177], v182 offset:1024
	ds_read_b128 v[178:181], v182 offset:2048
	ds_read_b128 v[182:185], v182 offset:3072
	s_add_u32 s62, s62, 0x100000
	s_addc_u32 s63, s63, 0
	s_mov_b32 m0, s44
	v_lshl_add_u64 v[224:225], s[62:63], 0, v[136:137]
	ds_read_b128 v[186:189], v153 offset:32768
	ds_read_b128 v[190:193], v153 offset:33792
	ds_read_b128 v[194:197], v153 offset:34816
	ds_read_b128 v[198:201], v153 offset:35840
	ds_read_b128 v[202:205], v153 offset:36864
	ds_read_b128 v[206:209], v153 offset:37888
	ds_read_b128 v[210:213], v153 offset:38912
	ds_read_b128 v[214:217], v153 offset:39936
	global_load_lds_dwordx4 v[224:225], off
	v_lshl_add_u64 v[224:225], s[62:63], 0, v[132:133]
	s_mov_b32 m0, s45
	s_nop 0
	global_load_lds_dwordx4 v[224:225], off
	s_waitcnt vmcnt(8)
	s_waitcnt lgkmcnt(0)
	s_setprio 1
	s_barrier
	v_mfma_f32_16x16x32_bf16 v[126:129], v[154:157], v[186:189], v[126:129]
	v_mfma_f32_16x16x32_bf16 v[118:121], v[162:165], v[186:189], v[118:121]
	v_mfma_f32_16x16x32_bf16 v[110:113], v[154:157], v[194:197], v[110:113]
	v_mfma_f32_16x16x32_bf16 v[102:105], v[162:165], v[194:197], v[102:105]
	v_mfma_f32_16x16x32_bf16 v[94:97], v[154:157], v[202:205], v[94:97]
	v_mfma_f32_16x16x32_bf16 v[86:89], v[162:165], v[202:205], v[86:89]
	v_mfma_f32_16x16x32_bf16 v[78:81], v[154:157], v[210:213], v[78:81]
	v_mfma_f32_16x16x32_bf16 v[70:73], v[162:165], v[210:213], v[70:73]
	v_mfma_f32_16x16x32_bf16 v[126:129], v[158:161], v[190:193], v[126:129]
	v_mfma_f32_16x16x32_bf16 v[118:121], v[166:169], v[190:193], v[118:121]
	v_mfma_f32_16x16x32_bf16 v[110:113], v[158:161], v[198:201], v[110:113]
	v_mfma_f32_16x16x32_bf16 v[102:105], v[166:169], v[198:201], v[102:105]
	v_mfma_f32_16x16x32_bf16 v[94:97], v[158:161], v[206:209], v[94:97]
	v_mfma_f32_16x16x32_bf16 v[86:89], v[166:169], v[206:209], v[86:89]
	v_mfma_f32_16x16x32_bf16 v[78:81], v[158:161], v[214:217], v[78:81]
	v_mfma_f32_16x16x32_bf16 v[70:73], v[166:169], v[214:217], v[70:73]
	s_setprio 0
	s_setprio 1
	v_mfma_f32_16x16x32_bf16 v[122:125], v[170:173], v[186:189], v[122:125]
	v_mfma_f32_16x16x32_bf16 v[114:117], v[178:181], v[186:189], v[114:117]
	v_mfma_f32_16x16x32_bf16 v[106:109], v[170:173], v[194:197], v[106:109]
	v_mfma_f32_16x16x32_bf16 v[98:101], v[178:181], v[194:197], v[98:101]
	v_mfma_f32_16x16x32_bf16 v[90:93], v[170:173], v[202:205], v[90:93]
	v_mfma_f32_16x16x32_bf16 v[82:85], v[178:181], v[202:205], v[82:85]
	v_mfma_f32_16x16x32_bf16 v[74:77], v[170:173], v[210:213], v[74:77]
	v_mfma_f32_16x16x32_bf16 v[66:69], v[178:181], v[210:213], v[66:69]
	v_mfma_f32_16x16x32_bf16 v[122:125], v[174:177], v[190:193], v[122:125]
	v_mfma_f32_16x16x32_bf16 v[114:117], v[182:185], v[190:193], v[114:117]
	v_mfma_f32_16x16x32_bf16 v[106:109], v[174:177], v[198:201], v[106:109]
	v_mfma_f32_16x16x32_bf16 v[98:101], v[182:185], v[198:201], v[98:101]
	v_mfma_f32_16x16x32_bf16 v[90:93], v[174:177], v[206:209], v[90:93]
	v_mfma_f32_16x16x32_bf16 v[82:85], v[182:185], v[206:209], v[82:85]
	v_mfma_f32_16x16x32_bf16 v[74:77], v[174:177], v[214:217], v[74:77]
	v_mfma_f32_16x16x32_bf16 v[66:69], v[182:185], v[214:217], v[66:69]
	s_setprio 0
	s_barrier
	s_add_i32 s62, s74, s15
	v_lshl_add_u64 v[146:147], v[146:147], 0, s[10:11]
	s_mov_b32 m0, s62
	ds_read_b128 v[186:189], v153 offset:49152
	ds_read_b128 v[190:193], v153 offset:50176
	ds_read_b128 v[194:197], v153 offset:51200
	ds_read_b128 v[198:201], v153 offset:52224
	ds_read_b128 v[202:205], v153 offset:53248
	ds_read_b128 v[206:209], v153 offset:54272
	ds_read_b128 v[210:213], v153 offset:55296
	ds_read_b128 v[214:217], v153 offset:56320
	global_load_lds_dwordx4 v[146:147], off
	s_add_i32 m0, s62, 0x2000
	s_add_u32 s58, s58, 0x100080
	v_lshl_add_u64 v[146:147], v[218:219], 0, s[10:11]
	s_addc_u32 s59, s59, 0
	s_add_i32 s62, s75, s15
	global_load_lds_dwordx4 v[146:147], off
	v_lshl_add_u64 v[146:147], s[58:59], 0, v[134:135]
	s_mov_b32 m0, s62
	s_nop 0
	global_load_lds_dwordx4 v[146:147], off
	v_lshl_add_u64 v[146:147], s[58:59], 0, v[130:131]
	s_add_i32 m0, s62, 0x2000
	s_nop 0
	global_load_lds_dwordx4 v[146:147], off
	v_lshl_add_u64 v[146:147], v[220:221], 0, s[10:11]
	s_mov_b32 m0, s47
	s_nop 0
	global_load_lds_dwordx4 v[146:147], off
	v_lshl_add_u64 v[146:147], v[222:223], 0, s[10:11]
	s_mov_b32 m0, s48
	s_nop 0
	global_load_lds_dwordx4 v[146:147], off
	s_waitcnt vmcnt(8)
	s_waitcnt lgkmcnt(0)
	s_setprio 1
	s_barrier
	v_mfma_f32_16x16x32_bf16 v[62:65], v[154:157], v[186:189], v[62:65]
	v_mfma_f32_16x16x32_bf16 v[54:57], v[162:165], v[186:189], v[54:57]
	v_mfma_f32_16x16x32_bf16 v[46:49], v[154:157], v[194:197], v[46:49]
	v_mfma_f32_16x16x32_bf16 v[38:41], v[162:165], v[194:197], v[38:41]
	v_mfma_f32_16x16x32_bf16 v[30:33], v[154:157], v[202:205], v[30:33]
	v_mfma_f32_16x16x32_bf16 v[22:25], v[162:165], v[202:205], v[22:25]
	v_mfma_f32_16x16x32_bf16 v[14:17], v[154:157], v[210:213], v[14:17]
	v_mfma_f32_16x16x32_bf16 v[6:9], v[162:165], v[210:213], v[6:9]
	v_mfma_f32_16x16x32_bf16 v[62:65], v[158:161], v[190:193], v[62:65]
	v_mfma_f32_16x16x32_bf16 v[54:57], v[166:169], v[190:193], v[54:57]
	v_mfma_f32_16x16x32_bf16 v[46:49], v[158:161], v[198:201], v[46:49]
	v_mfma_f32_16x16x32_bf16 v[38:41], v[166:169], v[198:201], v[38:41]
	v_mfma_f32_16x16x32_bf16 v[30:33], v[158:161], v[206:209], v[30:33]
	v_mfma_f32_16x16x32_bf16 v[22:25], v[166:169], v[206:209], v[22:25]
	v_mfma_f32_16x16x32_bf16 v[14:17], v[158:161], v[214:217], v[14:17]
	v_mfma_f32_16x16x32_bf16 v[6:9], v[166:169], v[214:217], v[6:9]
	s_setprio 0
	s_setprio 1
	v_mfma_f32_16x16x32_bf16 v[58:61], v[170:173], v[186:189], v[58:61]
	v_mfma_f32_16x16x32_bf16 v[50:53], v[178:181], v[186:189], v[50:53]
	v_mfma_f32_16x16x32_bf16 v[42:45], v[170:173], v[194:197], v[42:45]
	v_mfma_f32_16x16x32_bf16 v[34:37], v[178:181], v[194:197], v[34:37]
	v_mfma_f32_16x16x32_bf16 v[26:29], v[170:173], v[202:205], v[26:29]
	v_mfma_f32_16x16x32_bf16 v[18:21], v[178:181], v[202:205], v[18:21]
	v_mfma_f32_16x16x32_bf16 v[10:13], v[170:173], v[210:213], v[10:13]
	v_mfma_f32_16x16x32_bf16 v[2:5], v[178:181], v[210:213], v[2:5]
	v_mfma_f32_16x16x32_bf16 v[58:61], v[174:177], v[190:193], v[58:61]
	v_mfma_f32_16x16x32_bf16 v[50:53], v[182:185], v[190:193], v[50:53]
	v_mfma_f32_16x16x32_bf16 v[42:45], v[174:177], v[198:201], v[42:45]
	v_mfma_f32_16x16x32_bf16 v[34:37], v[182:185], v[198:201], v[34:37]
	v_mfma_f32_16x16x32_bf16 v[26:29], v[174:177], v[206:209], v[26:29]
	v_mfma_f32_16x16x32_bf16 v[18:21], v[182:185], v[206:209], v[18:21]
	v_mfma_f32_16x16x32_bf16 v[10:13], v[174:177], v[214:217], v[10:13]
	v_mfma_f32_16x16x32_bf16 v[2:5], v[182:185], v[214:217], v[2:5]
	s_setprio 0
	s_barrier
	s_add_i32 s73, s73, 2
	s_add_u32 s40, s40, 0x100
	s_addc_u32 s41, s41, 0
	s_add_u32 s71, s71, 0x100
	s_addc_u32 s72, s72, 0
	s_cmp_gt_u32 s73, 61
	s_cbranch_scc0 .LBB0_162
	s_and_b64 vcc, exec, s[12:13]
	s_cbranch_vccz .LBB0_165
	s_barrier

.LBB0_260:
	ds_read_b128 v[154:157], v150
	ds_read_b128 v[158:161], v150 offset:1024
	ds_read_b128 v[162:165], v150 offset:2048
	ds_read_b128 v[166:169], v150 offset:3072
	ds_read_b128 v[170:173], v151
	ds_read_b128 v[174:177], v151 offset:1024
	ds_read_b128 v[178:181], v151 offset:2048
	ds_read_b128 v[182:185], v151 offset:3072
	s_add_u32 s30, s28, 0x100
	s_addc_u32 s31, s29, 0
	s_cmpk_eq_i32 s74, 0xa8
	s_cselect_b32 s63, s5, s31
	s_cselect_b32 s62, s4, s30
	s_cselect_b32 s41, s27, s73
	s_cselect_b32 s40, s26, s72
	v_lshl_add_u64 v[146:147], s[28:29], 0, v[138:139]
	s_add_i32 m0, s15, 0xc000
	ds_read_b128 v[186:189], v152
	ds_read_b128 v[190:193], v152 offset:1024
	ds_read_b128 v[194:197], v152 offset:2048
	ds_read_b128 v[198:201], v152 offset:3072
	ds_read_b128 v[202:205], v152 offset:4096
	ds_read_b128 v[206:209], v152 offset:5120
	ds_read_b128 v[210:213], v152 offset:6144
	ds_read_b128 v[214:217], v152 offset:7168
	global_load_lds_dwordx4 v[146:147], off
	v_lshl_add_u64 v[146:147], s[28:29], 0, v[140:141]
	s_add_i32 m0, s15, 0xe000
	s_nop 0
	global_load_lds_dwordx4 v[146:147], off
	s_waitcnt vmcnt(8)
	s_waitcnt lgkmcnt(0)
	s_setprio 1
	s_barrier
	v_mfma_f32_16x16x32_bf16 v[126:129], v[154:157], v[186:189], v[126:129]
	v_mfma_f32_16x16x32_bf16 v[122:125], v[162:165], v[186:189], v[122:125]
	v_mfma_f32_16x16x32_bf16 v[118:121], v[154:157], v[194:197], v[118:121]
	v_mfma_f32_16x16x32_bf16 v[110:113], v[162:165], v[194:197], v[110:113]
	v_mfma_f32_16x16x32_bf16 v[102:105], v[154:157], v[202:205], v[102:105]
	v_mfma_f32_16x16x32_bf16 v[94:97], v[162:165], v[202:205], v[94:97]
	v_mfma_f32_16x16x32_bf16 v[82:85], v[154:157], v[210:213], v[82:85]
	v_mfma_f32_16x16x32_bf16 v[74:77], v[162:165], v[210:213], v[74:77]
	v_mfma_f32_16x16x32_bf16 v[126:129], v[158:161], v[190:193], v[126:129]
	v_mfma_f32_16x16x32_bf16 v[122:125], v[166:169], v[190:193], v[122:125]
	v_mfma_f32_16x16x32_bf16 v[118:121], v[158:161], v[198:201], v[118:121]
	v_mfma_f32_16x16x32_bf16 v[110:113], v[166:169], v[198:201], v[110:113]
	v_mfma_f32_16x16x32_bf16 v[102:105], v[158:161], v[206:209], v[102:105]
	v_mfma_f32_16x16x32_bf16 v[94:97], v[166:169], v[206:209], v[94:97]
	v_mfma_f32_16x16x32_bf16 v[82:85], v[158:161], v[214:217], v[82:85]
	v_mfma_f32_16x16x32_bf16 v[74:77], v[166:169], v[214:217], v[74:77]
	s_setprio 0
	s_setprio 1
	v_mfma_f32_16x16x32_bf16 v[114:117], v[170:173], v[186:189], v[114:117]
	v_mfma_f32_16x16x32_bf16 v[106:109], v[178:181], v[186:189], v[106:109]
	v_mfma_f32_16x16x32_bf16 v[98:101], v[170:173], v[194:197], v[98:101]
	v_mfma_f32_16x16x32_bf16 v[90:93], v[178:181], v[194:197], v[90:93]
	v_mfma_f32_16x16x32_bf16 v[86:89], v[170:173], v[202:205], v[86:89]
	v_mfma_f32_16x16x32_bf16 v[78:81], v[178:181], v[202:205], v[78:81]
	v_mfma_f32_16x16x32_bf16 v[70:73], v[170:173], v[210:213], v[70:73]
	v_mfma_f32_16x16x32_bf16 v[66:69], v[178:181], v[210:213], v[66:69]
	v_mfma_f32_16x16x32_bf16 v[114:117], v[174:177], v[190:193], v[114:117]
	v_mfma_f32_16x16x32_bf16 v[106:109], v[182:185], v[190:193], v[106:109]
	v_mfma_f32_16x16x32_bf16 v[98:101], v[174:177], v[198:201], v[98:101]
	v_mfma_f32_16x16x32_bf16 v[90:93], v[182:185], v[198:201], v[90:93]
	v_mfma_f32_16x16x32_bf16 v[86:89], v[174:177], v[206:209], v[86:89]
	v_mfma_f32_16x16x32_bf16 v[78:81], v[182:185], v[206:209], v[78:81]
	v_mfma_f32_16x16x32_bf16 v[70:73], v[174:177], v[214:217], v[70:73]
	v_mfma_f32_16x16x32_bf16 v[66:69], v[182:185], v[214:217], v[66:69]
	s_setprio 0
	s_barrier
	s_add_i32 s28, s50, s3
	v_lshl_add_u64 v[146:147], s[40:41], 0, v[132:133]
	s_mov_b32 m0, s28
	ds_read_b128 v[186:189], v152 offset:16384
	ds_read_b128 v[190:193], v152 offset:17408
	ds_read_b128 v[194:197], v152 offset:18432
	ds_read_b128 v[198:201], v152 offset:19456
	ds_read_b128 v[202:205], v152 offset:20480
	ds_read_b128 v[206:209], v152 offset:21504
	ds_read_b128 v[210:213], v152 offset:22528
	ds_read_b128 v[214:217], v152 offset:23552
	global_load_lds_dwordx4 v[146:147], off
	s_add_i32 m0, s28, 0x2000
	s_add_u32 s28, s40, 0x2b0000
	v_lshl_add_u64 v[218:219], s[40:41], 0, v[136:137]
	s_addc_u32 s29, s41, 0
	s_add_i32 s75, s51, s3
	global_load_lds_dwordx4 v[218:219], off
	v_lshl_add_u64 v[220:221], s[28:29], 0, v[132:133]
	s_mov_b32 m0, s75
	v_lshl_add_u64 v[222:223], s[62:63], 0, v[134:135]
	global_load_lds_dwordx4 v[220:221], off
	v_lshl_add_u64 v[220:221], s[28:29], 0, v[136:137]
	s_add_i32 m0, s75, 0x2000
	s_nop 0
	global_load_lds_dwordx4 v[220:221], off
	v_lshl_add_u64 v[220:221], s[62:63], 0, v[130:131]
	s_mov_b32 m0, s15
	s_nop 0
	global_load_lds_dwordx4 v[220:221], off
	s_mov_b32 m0, s36
	s_nop 0
	global_load_lds_dwordx4 v[222:223], off
	s_waitcnt vmcnt(8)
	s_waitcnt lgkmcnt(0)
	s_setprio 1
	s_barrier
	v_mfma_f32_16x16x32_bf16 v[62:65], v[154:157], v[186:189], v[62:65]
	v_mfma_f32_16x16x32_bf16 v[58:61], v[162:165], v[186:189], v[58:61]
	v_mfma_f32_16x16x32_bf16 v[54:57], v[154:157], v[194:197], v[54:57]
	v_mfma_f32_16x16x32_bf16 v[46:49], v[162:165], v[194:197], v[46:49]
	v_mfma_f32_16x16x32_bf16 v[38:41], v[154:157], v[202:205], v[38:41]
	v_mfma_f32_16x16x32_bf16 v[30:33], v[162:165], v[202:205], v[30:33]
	v_mfma_f32_16x16x32_bf16 v[22:25], v[154:157], v[210:213], v[22:25]
	v_mfma_f32_16x16x32_bf16 v[14:17], v[162:165], v[210:213], v[14:17]
	v_mfma_f32_16x16x32_bf16 v[62:65], v[158:161], v[190:193], v[62:65]
	v_mfma_f32_16x16x32_bf16 v[58:61], v[166:169], v[190:193], v[58:61]
	v_mfma_f32_16x16x32_bf16 v[54:57], v[158:161], v[198:201], v[54:57]
	v_mfma_f32_16x16x32_bf16 v[46:49], v[166:169], v[198:201], v[46:49]
	v_mfma_f32_16x16x32_bf16 v[38:41], v[158:161], v[206:209], v[38:41]
	v_mfma_f32_16x16x32_bf16 v[30:33], v[166:169], v[206:209], v[30:33]
	v_mfma_f32_16x16x32_bf16 v[22:25], v[158:161], v[214:217], v[22:25]
	v_mfma_f32_16x16x32_bf16 v[14:17], v[166:169], v[214:217], v[14:17]
	s_setprio 0
	s_setprio 1
	v_mfma_f32_16x16x32_bf16 v[50:53], v[170:173], v[186:189], v[50:53]
	v_mfma_f32_16x16x32_bf16 v[42:45], v[178:181], v[186:189], v[42:45]
	v_mfma_f32_16x16x32_bf16 v[34:37], v[170:173], v[194:197], v[34:37]
	v_mfma_f32_16x16x32_bf16 v[26:29], v[178:181], v[194:197], v[26:29]
	v_mfma_f32_16x16x32_bf16 v[18:21], v[170:173], v[202:205], v[18:21]
	v_mfma_f32_16x16x32_bf16 v[10:13], v[178:181], v[202:205], v[10:13]
	v_mfma_f32_16x16x32_bf16 v[6:9], v[170:173], v[210:213], v[6:9]
	v_mfma_f32_16x16x32_bf16 v[2:5], v[178:181], v[210:213], v[2:5]
	v_mfma_f32_16x16x32_bf16 v[50:53], v[174:177], v[190:193], v[50:53]
	v_mfma_f32_16x16x32_bf16 v[42:45], v[182:185], v[190:193], v[42:45]
	v_mfma_f32_16x16x32_bf16 v[34:37], v[174:177], v[198:201], v[34:37]
	v_mfma_f32_16x16x32_bf16 v[26:29], v[182:185], v[198:201], v[26:29]
	v_mfma_f32_16x16x32_bf16 v[18:21], v[174:177], v[206:209], v[18:21]
	v_mfma_f32_16x16x32_bf16 v[10:13], v[182:185], v[206:209], v[10:13]
	v_mfma_f32_16x16x32_bf16 v[6:9], v[174:177], v[214:217], v[6:9]
	v_mfma_f32_16x16x32_bf16 v[2:5], v[182:185], v[214:217], v[2:5]
	s_setprio 0
	s_barrier
	s_add_i32 s75, 0, 0x18000
	v_add_u32_e32 v153, s75, v148
	s_add_i32 s76, 0, 0x1c000
	ds_read_b128 v[154:157], v153
	ds_read_b128 v[158:161], v153 offset:1024
	ds_read_b128 v[162:165], v153 offset:2048
	ds_read_b128 v[166:169], v153 offset:3072
	v_add_u32_e32 v153, s76, v148
	ds_read_b128 v[170:173], v153
	ds_read_b128 v[174:177], v153 offset:1024
	ds_read_b128 v[178:181], v153 offset:2048
	ds_read_b128 v[182:185], v153 offset:3072
	s_add_u32 s28, s62, 0x2b0000
	s_addc_u32 s29, s63, 0
	s_mov_b32 m0, s37
	v_lshl_add_u64 v[224:225], s[28:29], 0, v[130:131]
	ds_read_b128 v[186:189], v152 offset:32768
	ds_read_b128 v[190:193], v152 offset:33792
	ds_read_b128 v[194:197], v152 offset:34816
	ds_read_b128 v[198:201], v152 offset:35840
	ds_read_b128 v[202:205], v152 offset:36864
	ds_read_b128 v[206:209], v152 offset:37888
	ds_read_b128 v[210:213], v152 offset:38912
	ds_read_b128 v[214:217], v152 offset:39936
	global_load_lds_dwordx4 v[224:225], off
	v_lshl_add_u64 v[224:225], s[28:29], 0, v[134:135]
	s_mov_b32 m0, s42
	s_nop 0
	global_load_lds_dwordx4 v[224:225], off
	s_waitcnt vmcnt(8)
	s_waitcnt lgkmcnt(0)
	s_setprio 1
	s_barrier
	v_mfma_f32_16x16x32_bf16 v[126:129], v[154:157], v[186:189], v[126:129]
	v_mfma_f32_16x16x32_bf16 v[122:125], v[162:165], v[186:189], v[122:125]
	v_mfma_f32_16x16x32_bf16 v[118:121], v[154:157], v[194:197], v[118:121]
	v_mfma_f32_16x16x32_bf16 v[110:113], v[162:165], v[194:197], v[110:113]
	v_mfma_f32_16x16x32_bf16 v[102:105], v[154:157], v[202:205], v[102:105]
	v_mfma_f32_16x16x32_bf16 v[94:97], v[162:165], v[202:205], v[94:97]
	v_mfma_f32_16x16x32_bf16 v[82:85], v[154:157], v[210:213], v[82:85]
	v_mfma_f32_16x16x32_bf16 v[74:77], v[162:165], v[210:213], v[74:77]
	v_mfma_f32_16x16x32_bf16 v[126:129], v[158:161], v[190:193], v[126:129]
	v_mfma_f32_16x16x32_bf16 v[122:125], v[166:169], v[190:193], v[122:125]
	v_mfma_f32_16x16x32_bf16 v[118:121], v[158:161], v[198:201], v[118:121]
	v_mfma_f32_16x16x32_bf16 v[110:113], v[166:169], v[198:201], v[110:113]
	v_mfma_f32_16x16x32_bf16 v[102:105], v[158:161], v[206:209], v[102:105]
	v_mfma_f32_16x16x32_bf16 v[94:97], v[166:169], v[206:209], v[94:97]
	v_mfma_f32_16x16x32_bf16 v[82:85], v[158:161], v[214:217], v[82:85]
	v_mfma_f32_16x16x32_bf16 v[74:77], v[166:169], v[214:217], v[74:77]
	s_setprio 0
	s_setprio 1
	v_mfma_f32_16x16x32_bf16 v[114:117], v[170:173], v[186:189], v[114:117]
	v_mfma_f32_16x16x32_bf16 v[106:109], v[178:181], v[186:189], v[106:109]
	v_mfma_f32_16x16x32_bf16 v[98:101], v[170:173], v[194:197], v[98:101]
	v_mfma_f32_16x16x32_bf16 v[90:93], v[178:181], v[194:197], v[90:93]
	v_mfma_f32_16x16x32_bf16 v[86:89], v[170:173], v[202:205], v[86:89]
	v_mfma_f32_16x16x32_bf16 v[78:81], v[178:181], v[202:205], v[78:81]
	v_mfma_f32_16x16x32_bf16 v[70:73], v[170:173], v[210:213], v[70:73]
	v_mfma_f32_16x16x32_bf16 v[66:69], v[178:181], v[210:213], v[66:69]
	v_mfma_f32_16x16x32_bf16 v[114:117], v[174:177], v[190:193], v[114:117]
	v_mfma_f32_16x16x32_bf16 v[106:109], v[182:185], v[190:193], v[106:109]
	v_mfma_f32_16x16x32_bf16 v[98:101], v[174:177], v[198:201], v[98:101]
	v_mfma_f32_16x16x32_bf16 v[90:93], v[182:185], v[198:201], v[90:93]
	v_mfma_f32_16x16x32_bf16 v[86:89], v[174:177], v[206:209], v[86:89]
	v_mfma_f32_16x16x32_bf16 v[78:81], v[182:185], v[206:209], v[78:81]
	v_mfma_f32_16x16x32_bf16 v[70:73], v[174:177], v[214:217], v[70:73]
	v_mfma_f32_16x16x32_bf16 v[66:69], v[182:185], v[214:217], v[66:69]
	s_setprio 0
	s_barrier
	s_add_i32 s28, s75, s3
	v_lshl_add_u64 v[146:147], v[146:147], 0, s[22:23]
	s_mov_b32 m0, s28
	ds_read_b128 v[186:189], v152 offset:49152
	ds_read_b128 v[190:193], v152 offset:50176
	ds_read_b128 v[194:197], v152 offset:51200
	ds_read_b128 v[198:201], v152 offset:52224
	ds_read_b128 v[202:205], v152 offset:53248
	ds_read_b128 v[206:209], v152 offset:54272
	ds_read_b128 v[210:213], v152 offset:55296
	ds_read_b128 v[214:217], v152 offset:56320
	global_load_lds_dwordx4 v[146:147], off
	s_add_i32 m0, s28, 0x2000
	s_add_u32 s28, s40, 0x2b0080
	v_lshl_add_u64 v[146:147], v[218:219], 0, s[22:23]
	s_addc_u32 s29, s41, 0
	s_add_i32 s40, s76, s3
	global_load_lds_dwordx4 v[146:147], off
	v_lshl_add_u64 v[146:147], s[28:29], 0, v[132:133]
	s_mov_b32 m0, s40
	s_nop 0
	global_load_lds_dwordx4 v[146:147], off
	v_lshl_add_u64 v[146:147], s[28:29], 0, v[136:137]
	s_add_i32 m0, s40, 0x2000
	s_nop 0
	global_load_lds_dwordx4 v[146:147], off
	v_lshl_add_u64 v[146:147], v[220:221], 0, s[22:23]
	s_mov_b32 m0, s44
	s_nop 0
	global_load_lds_dwordx4 v[146:147], off
	v_lshl_add_u64 v[146:147], v[222:223], 0, s[22:23]
	s_mov_b32 m0, s45
	s_nop 0
	global_load_lds_dwordx4 v[146:147], off
	s_waitcnt vmcnt(8)
	s_waitcnt lgkmcnt(0)
	s_setprio 1
	s_barrier
	v_mfma_f32_16x16x32_bf16 v[62:65], v[154:157], v[186:189], v[62:65]
	v_mfma_f32_16x16x32_bf16 v[58:61], v[162:165], v[186:189], v[58:61]
	v_mfma_f32_16x16x32_bf16 v[54:57], v[154:157], v[194:197], v[54:57]
	v_mfma_f32_16x16x32_bf16 v[46:49], v[162:165], v[194:197], v[46:49]
	v_mfma_f32_16x16x32_bf16 v[38:41], v[154:157], v[202:205], v[38:41]
	v_mfma_f32_16x16x32_bf16 v[30:33], v[162:165], v[202:205], v[30:33]
	v_mfma_f32_16x16x32_bf16 v[22:25], v[154:157], v[210:213], v[22:25]
	v_mfma_f32_16x16x32_bf16 v[14:17], v[162:165], v[210:213], v[14:17]
	v_mfma_f32_16x16x32_bf16 v[62:65], v[158:161], v[190:193], v[62:65]
	v_mfma_f32_16x16x32_bf16 v[58:61], v[166:169], v[190:193], v[58:61]
	v_mfma_f32_16x16x32_bf16 v[54:57], v[158:161], v[198:201], v[54:57]
	v_mfma_f32_16x16x32_bf16 v[46:49], v[166:169], v[198:201], v[46:49]
	v_mfma_f32_16x16x32_bf16 v[38:41], v[158:161], v[206:209], v[38:41]
	v_mfma_f32_16x16x32_bf16 v[30:33], v[166:169], v[206:209], v[30:33]
	v_mfma_f32_16x16x32_bf16 v[22:25], v[158:161], v[214:217], v[22:25]
	v_mfma_f32_16x16x32_bf16 v[14:17], v[166:169], v[214:217], v[14:17]
	s_setprio 0
	s_setprio 1
	v_mfma_f32_16x16x32_bf16 v[50:53], v[170:173], v[186:189], v[50:53]
	v_mfma_f32_16x16x32_bf16 v[42:45], v[178:181], v[186:189], v[42:45]
	v_mfma_f32_16x16x32_bf16 v[34:37], v[170:173], v[194:197], v[34:37]
	v_mfma_f32_16x16x32_bf16 v[26:29], v[178:181], v[194:197], v[26:29]
	v_mfma_f32_16x16x32_bf16 v[18:21], v[170:173], v[202:205], v[18:21]
	v_mfma_f32_16x16x32_bf16 v[10:13], v[178:181], v[202:205], v[10:13]
	v_mfma_f32_16x16x32_bf16 v[6:9], v[170:173], v[210:213], v[6:9]
	v_mfma_f32_16x16x32_bf16 v[2:5], v[178:181], v[210:213], v[2:5]
	v_mfma_f32_16x16x32_bf16 v[50:53], v[174:177], v[190:193], v[50:53]
	v_mfma_f32_16x16x32_bf16 v[42:45], v[182:185], v[190:193], v[42:45]
	v_mfma_f32_16x16x32_bf16 v[34:37], v[174:177], v[198:201], v[34:37]
	v_mfma_f32_16x16x32_bf16 v[26:29], v[182:185], v[198:201], v[26:29]
	v_mfma_f32_16x16x32_bf16 v[18:21], v[174:177], v[206:209], v[18:21]
	v_mfma_f32_16x16x32_bf16 v[10:13], v[182:185], v[206:209], v[10:13]
	v_mfma_f32_16x16x32_bf16 v[6:9], v[174:177], v[214:217], v[6:9]
	v_mfma_f32_16x16x32_bf16 v[2:5], v[182:185], v[214:217], v[2:5]
	s_setprio 0
	s_barrier
	s_add_i32 s74, s74, 2
	s_add_u32 s72, s72, 0x100
	s_addc_u32 s73, s73, 0
	s_cmpk_gt_u32 s74, 0xa9
	s_mov_b64 s[28:29], s[30:31]
	s_cbranch_scc0 .LBB0_260
	s_and_b64 vcc, exec, s[24:25]
	s_cbranch_vccz .LBB0_263
	s_barrier

.LBB0_387:
	ds_read_b128 v[152:155], v148
	ds_read_b128 v[156:159], v148 offset:1024
	ds_read_b128 v[160:163], v148 offset:2048
	ds_read_b128 v[164:167], v148 offset:3072
	ds_read_b128 v[168:171], v149
	ds_read_b128 v[172:175], v149 offset:1024
	ds_read_b128 v[176:179], v149 offset:2048
	ds_read_b128 v[180:183], v149 offset:3072
	s_add_u32 s40, s30, 0xfff00080
	s_addc_u32 s41, s31, -1
	s_cmp_eq_u32 s71, 60
	s_cselect_b32 s69, s23, s41
	s_cselect_b32 s68, s63, s40
	s_cselect_b32 s41, s13, s70
	s_cselect_b32 s40, s66, s67
	v_lshl_add_u64 v[144:145], s[30:31], 0, v[134:135]
	s_add_i32 m0, s29, 0xc000
	ds_read_b128 v[184:187], v150
	ds_read_b128 v[188:191], v150 offset:1024
	ds_read_b128 v[192:195], v150 offset:2048
	ds_read_b128 v[196:199], v150 offset:3072
	ds_read_b128 v[200:203], v150 offset:4096
	ds_read_b128 v[204:207], v150 offset:5120
	ds_read_b128 v[208:211], v150 offset:6144
	ds_read_b128 v[212:215], v150 offset:7168
	global_load_lds_dwordx4 v[144:145], off
	v_lshl_add_u64 v[144:145], s[30:31], 0, v[136:137]
	s_add_i32 m0, s29, 0xe000
	s_nop 0
	global_load_lds_dwordx4 v[144:145], off
	s_waitcnt vmcnt(8)
	s_waitcnt lgkmcnt(0)
	s_setprio 1
	s_barrier
	v_mfma_f32_16x16x32_bf16 v[126:129], v[152:155], v[184:187], v[126:129]
	v_mfma_f32_16x16x32_bf16 v[122:125], v[160:163], v[184:187], v[122:125]
	v_mfma_f32_16x16x32_bf16 v[114:117], v[152:155], v[192:195], v[114:117]
	v_mfma_f32_16x16x32_bf16 v[106:109], v[160:163], v[192:195], v[106:109]
	v_mfma_f32_16x16x32_bf16 v[98:101], v[152:155], v[200:203], v[98:101]
	v_mfma_f32_16x16x32_bf16 v[90:93], v[160:163], v[200:203], v[90:93]
	v_mfma_f32_16x16x32_bf16 v[82:85], v[152:155], v[208:211], v[82:85]
	v_mfma_f32_16x16x32_bf16 v[74:77], v[160:163], v[208:211], v[74:77]
	v_mfma_f32_16x16x32_bf16 v[126:129], v[156:159], v[188:191], v[126:129]
	v_mfma_f32_16x16x32_bf16 v[122:125], v[164:167], v[188:191], v[122:125]
	v_mfma_f32_16x16x32_bf16 v[114:117], v[156:159], v[196:199], v[114:117]
	v_mfma_f32_16x16x32_bf16 v[106:109], v[164:167], v[196:199], v[106:109]
	v_mfma_f32_16x16x32_bf16 v[98:101], v[156:159], v[204:207], v[98:101]
	v_mfma_f32_16x16x32_bf16 v[90:93], v[164:167], v[204:207], v[90:93]
	v_mfma_f32_16x16x32_bf16 v[82:85], v[156:159], v[212:215], v[82:85]
	v_mfma_f32_16x16x32_bf16 v[74:77], v[164:167], v[212:215], v[74:77]
	s_setprio 0
	s_setprio 1
	v_mfma_f32_16x16x32_bf16 v[118:121], v[168:171], v[184:187], v[118:121]
	v_mfma_f32_16x16x32_bf16 v[110:113], v[176:179], v[184:187], v[110:113]
	v_mfma_f32_16x16x32_bf16 v[102:105], v[168:171], v[192:195], v[102:105]
	v_mfma_f32_16x16x32_bf16 v[94:97], v[176:179], v[192:195], v[94:97]
	v_mfma_f32_16x16x32_bf16 v[86:89], v[168:171], v[200:203], v[86:89]
	v_mfma_f32_16x16x32_bf16 v[78:81], v[176:179], v[200:203], v[78:81]
	v_mfma_f32_16x16x32_bf16 v[70:73], v[168:171], v[208:211], v[70:73]
	v_mfma_f32_16x16x32_bf16 v[66:69], v[176:179], v[208:211], v[66:69]
	v_mfma_f32_16x16x32_bf16 v[118:121], v[172:175], v[188:191], v[118:121]
	v_mfma_f32_16x16x32_bf16 v[110:113], v[180:183], v[188:191], v[110:113]
	v_mfma_f32_16x16x32_bf16 v[102:105], v[172:175], v[196:199], v[102:105]
	v_mfma_f32_16x16x32_bf16 v[94:97], v[180:183], v[196:199], v[94:97]
	v_mfma_f32_16x16x32_bf16 v[86:89], v[172:175], v[204:207], v[86:89]
	v_mfma_f32_16x16x32_bf16 v[78:81], v[180:183], v[204:207], v[78:81]
	v_mfma_f32_16x16x32_bf16 v[70:73], v[172:175], v[212:215], v[70:73]
	v_mfma_f32_16x16x32_bf16 v[66:69], v[180:183], v[212:215], v[66:69]
	s_setprio 0
	s_barrier
	s_add_i32 s72, s50, s36
	v_lshl_add_u64 v[144:145], s[40:41], 0, v[132:133]
	s_mov_b32 m0, s72
	ds_read_b128 v[184:187], v150 offset:16384
	ds_read_b128 v[188:191], v150 offset:17408
	ds_read_b128 v[192:195], v150 offset:18432
	ds_read_b128 v[196:199], v150 offset:19456
	ds_read_b128 v[200:203], v150 offset:20480
	ds_read_b128 v[204:207], v150 offset:21504
	ds_read_b128 v[208:211], v150 offset:22528
	ds_read_b128 v[212:215], v150 offset:23552
	global_load_lds_dwordx4 v[144:145], off
	s_add_i32 m0, s72, 0x2000
	s_add_u32 s72, s40, 0x100000
	v_lshl_add_u64 v[216:217], s[40:41], 0, v[130:131]
	s_addc_u32 s73, s41, 0
	s_add_i32 s74, s51, s36
	global_load_lds_dwordx4 v[216:217], off
	v_lshl_add_u64 v[218:219], s[72:73], 0, v[132:133]
	s_mov_b32 m0, s74
	v_lshl_add_u64 v[220:221], s[68:69], 0, v[130:131]
	global_load_lds_dwordx4 v[218:219], off
	v_lshl_add_u64 v[218:219], s[72:73], 0, v[130:131]
	s_add_i32 m0, s74, 0x2000
	s_nop 0
	global_load_lds_dwordx4 v[218:219], off
	v_lshl_add_u64 v[218:219], s[68:69], 0, v[132:133]
	s_mov_b32 m0, s29
	s_nop 0
	global_load_lds_dwordx4 v[218:219], off
	s_mov_b32 m0, s43
	s_nop 0
	global_load_lds_dwordx4 v[220:221], off
	s_waitcnt vmcnt(8)
	s_waitcnt lgkmcnt(0)
	s_setprio 1
	s_barrier
	v_mfma_f32_16x16x32_bf16 v[62:65], v[152:155], v[184:187], v[62:65]
	v_mfma_f32_16x16x32_bf16 v[58:61], v[160:163], v[184:187], v[58:61]
	v_mfma_f32_16x16x32_bf16 v[50:53], v[152:155], v[192:195], v[50:53]
	v_mfma_f32_16x16x32_bf16 v[42:45], v[160:163], v[192:195], v[42:45]
	v_mfma_f32_16x16x32_bf16 v[34:37], v[152:155], v[200:203], v[34:37]
	v_mfma_f32_16x16x32_bf16 v[26:29], v[160:163], v[200:203], v[26:29]
	v_mfma_f32_16x16x32_bf16 v[18:21], v[152:155], v[208:211], v[18:21]
	v_mfma_f32_16x16x32_bf16 v[10:13], v[160:163], v[208:211], v[10:13]
	v_mfma_f32_16x16x32_bf16 v[62:65], v[156:159], v[188:191], v[62:65]
	v_mfma_f32_16x16x32_bf16 v[58:61], v[164:167], v[188:191], v[58:61]
	v_mfma_f32_16x16x32_bf16 v[50:53], v[156:159], v[196:199], v[50:53]
	v_mfma_f32_16x16x32_bf16 v[42:45], v[164:167], v[196:199], v[42:45]
	v_mfma_f32_16x16x32_bf16 v[34:37], v[156:159], v[204:207], v[34:37]
	v_mfma_f32_16x16x32_bf16 v[26:29], v[164:167], v[204:207], v[26:29]
	v_mfma_f32_16x16x32_bf16 v[18:21], v[156:159], v[212:215], v[18:21]
	v_mfma_f32_16x16x32_bf16 v[10:13], v[164:167], v[212:215], v[10:13]
	s_setprio 0
	s_setprio 1
	v_mfma_f32_16x16x32_bf16 v[54:57], v[168:171], v[184:187], v[54:57]
	v_mfma_f32_16x16x32_bf16 v[46:49], v[176:179], v[184:187], v[46:49]
	v_mfma_f32_16x16x32_bf16 v[38:41], v[168:171], v[192:195], v[38:41]
	v_mfma_f32_16x16x32_bf16 v[30:33], v[176:179], v[192:195], v[30:33]
	v_mfma_f32_16x16x32_bf16 v[22:25], v[168:171], v[200:203], v[22:25]
	v_mfma_f32_16x16x32_bf16 v[14:17], v[176:179], v[200:203], v[14:17]
	v_mfma_f32_16x16x32_bf16 v[6:9], v[168:171], v[208:211], v[6:9]
	v_mfma_f32_16x16x32_bf16 v[2:5], v[176:179], v[208:211], v[2:5]
	v_mfma_f32_16x16x32_bf16 v[54:57], v[172:175], v[188:191], v[54:57]
	v_mfma_f32_16x16x32_bf16 v[46:49], v[180:183], v[188:191], v[46:49]
	v_mfma_f32_16x16x32_bf16 v[38:41], v[172:175], v[196:199], v[38:41]
	v_mfma_f32_16x16x32_bf16 v[30:33], v[180:183], v[196:199], v[30:33]
	v_mfma_f32_16x16x32_bf16 v[22:25], v[172:175], v[204:207], v[22:25]
	v_mfma_f32_16x16x32_bf16 v[14:17], v[180:183], v[204:207], v[14:17]
	v_mfma_f32_16x16x32_bf16 v[6:9], v[172:175], v[212:215], v[6:9]
	v_mfma_f32_16x16x32_bf16 v[2:5], v[180:183], v[212:215], v[2:5]
	s_setprio 0
	s_barrier
	s_add_i32 s72, 0, 0x18000
	v_add_u32_e32 v142, s72, v146
	s_add_i32 s73, 0, 0x1c000
	ds_read_b128 v[152:155], v142
	ds_read_b128 v[156:159], v142 offset:1024
	ds_read_b128 v[160:163], v142 offset:2048
	ds_read_b128 v[164:167], v142 offset:3072
	v_add_u32_e32 v142, s73, v146
	ds_read_b128 v[168:171], v142
	ds_read_b128 v[172:175], v142 offset:1024
	ds_read_b128 v[176:179], v142 offset:2048
	ds_read_b128 v[180:183], v142 offset:3072
	s_add_u32 s68, s68, 0x100000
	s_addc_u32 s69, s69, 0
	s_mov_b32 m0, s44
	v_lshl_add_u64 v[222:223], s[68:69], 0, v[132:133]
	ds_read_b128 v[184:187], v150 offset:32768
	ds_read_b128 v[188:191], v150 offset:33792
	ds_read_b128 v[192:195], v150 offset:34816
	ds_read_b128 v[196:199], v150 offset:35840
	ds_read_b128 v[200:203], v150 offset:36864
	ds_read_b128 v[204:207], v150 offset:37888
	ds_read_b128 v[208:211], v150 offset:38912
	ds_read_b128 v[212:215], v150 offset:39936
	global_load_lds_dwordx4 v[222:223], off
	v_lshl_add_u64 v[222:223], s[68:69], 0, v[130:131]
	s_mov_b32 m0, s45
	s_nop 0
	global_load_lds_dwordx4 v[222:223], off
	s_waitcnt vmcnt(8)
	s_waitcnt lgkmcnt(0)
	s_setprio 1
	s_barrier
	v_mfma_f32_16x16x32_bf16 v[126:129], v[152:155], v[184:187], v[126:129]
	v_mfma_f32_16x16x32_bf16 v[122:125], v[160:163], v[184:187], v[122:125]
	v_mfma_f32_16x16x32_bf16 v[114:117], v[152:155], v[192:195], v[114:117]
	v_mfma_f32_16x16x32_bf16 v[106:109], v[160:163], v[192:195], v[106:109]
	v_mfma_f32_16x16x32_bf16 v[98:101], v[152:155], v[200:203], v[98:101]
	v_mfma_f32_16x16x32_bf16 v[90:93], v[160:163], v[200:203], v[90:93]
	v_mfma_f32_16x16x32_bf16 v[82:85], v[152:155], v[208:211], v[82:85]
	v_mfma_f32_16x16x32_bf16 v[74:77], v[160:163], v[208:211], v[74:77]
	v_mfma_f32_16x16x32_bf16 v[126:129], v[156:159], v[188:191], v[126:129]
	v_mfma_f32_16x16x32_bf16 v[122:125], v[164:167], v[188:191], v[122:125]
	v_mfma_f32_16x16x32_bf16 v[114:117], v[156:159], v[196:199], v[114:117]
	v_mfma_f32_16x16x32_bf16 v[106:109], v[164:167], v[196:199], v[106:109]
	v_mfma_f32_16x16x32_bf16 v[98:101], v[156:159], v[204:207], v[98:101]
	v_mfma_f32_16x16x32_bf16 v[90:93], v[164:167], v[204:207], v[90:93]
	v_mfma_f32_16x16x32_bf16 v[82:85], v[156:159], v[212:215], v[82:85]
	v_mfma_f32_16x16x32_bf16 v[74:77], v[164:167], v[212:215], v[74:77]
	s_setprio 0
	s_setprio 1
	v_mfma_f32_16x16x32_bf16 v[118:121], v[168:171], v[184:187], v[118:121]
	v_mfma_f32_16x16x32_bf16 v[110:113], v[176:179], v[184:187], v[110:113]
	v_mfma_f32_16x16x32_bf16 v[102:105], v[168:171], v[192:195], v[102:105]
	v_mfma_f32_16x16x32_bf16 v[94:97], v[176:179], v[192:195], v[94:97]
	v_mfma_f32_16x16x32_bf16 v[86:89], v[168:171], v[200:203], v[86:89]
	v_mfma_f32_16x16x32_bf16 v[78:81], v[176:179], v[200:203], v[78:81]
	v_mfma_f32_16x16x32_bf16 v[70:73], v[168:171], v[208:211], v[70:73]
	v_mfma_f32_16x16x32_bf16 v[66:69], v[176:179], v[208:211], v[66:69]
	v_mfma_f32_16x16x32_bf16 v[118:121], v[172:175], v[188:191], v[118:121]
	v_mfma_f32_16x16x32_bf16 v[110:113], v[180:183], v[188:191], v[110:113]
	v_mfma_f32_16x16x32_bf16 v[102:105], v[172:175], v[196:199], v[102:105]
	v_mfma_f32_16x16x32_bf16 v[94:97], v[180:183], v[196:199], v[94:97]
	v_mfma_f32_16x16x32_bf16 v[86:89], v[172:175], v[204:207], v[86:89]
	v_mfma_f32_16x16x32_bf16 v[78:81], v[180:183], v[204:207], v[78:81]
	v_mfma_f32_16x16x32_bf16 v[70:73], v[172:175], v[212:215], v[70:73]
	v_mfma_f32_16x16x32_bf16 v[66:69], v[180:183], v[212:215], v[66:69]
	s_setprio 0
	s_barrier
	s_add_i32 s68, s72, s36
	v_lshl_add_u64 v[144:145], v[144:145], 0, s[8:9]
	s_mov_b32 m0, s68
	ds_read_b128 v[184:187], v150 offset:49152
	ds_read_b128 v[188:191], v150 offset:50176
	ds_read_b128 v[192:195], v150 offset:51200
	ds_read_b128 v[196:199], v150 offset:52224
	ds_read_b128 v[200:203], v150 offset:53248
	ds_read_b128 v[204:207], v150 offset:54272
	ds_read_b128 v[208:211], v150 offset:55296
	ds_read_b128 v[212:215], v150 offset:56320
	global_load_lds_dwordx4 v[144:145], off
	s_add_i32 m0, s68, 0x2000
	s_add_u32 s40, s40, 0x100080
	v_lshl_add_u64 v[144:145], v[216:217], 0, s[8:9]
	s_addc_u32 s41, s41, 0
	s_add_i32 s68, s73, s36
	global_load_lds_dwordx4 v[144:145], off
	v_lshl_add_u64 v[144:145], s[40:41], 0, v[132:133]
	s_mov_b32 m0, s68
	s_nop 0
	global_load_lds_dwordx4 v[144:145], off
	v_lshl_add_u64 v[144:145], s[40:41], 0, v[130:131]
	s_add_i32 m0, s68, 0x2000
	s_nop 0
	global_load_lds_dwordx4 v[144:145], off
	v_lshl_add_u64 v[144:145], v[218:219], 0, s[8:9]
	s_mov_b32 m0, s47
	s_nop 0
	global_load_lds_dwordx4 v[144:145], off
	v_lshl_add_u64 v[144:145], v[220:221], 0, s[8:9]
	s_mov_b32 m0, s48
	s_nop 0
	global_load_lds_dwordx4 v[144:145], off
	s_waitcnt vmcnt(8)
	s_waitcnt lgkmcnt(0)
	s_setprio 1
	s_barrier
	v_mfma_f32_16x16x32_bf16 v[62:65], v[152:155], v[184:187], v[62:65]
	v_mfma_f32_16x16x32_bf16 v[58:61], v[160:163], v[184:187], v[58:61]
	v_mfma_f32_16x16x32_bf16 v[50:53], v[152:155], v[192:195], v[50:53]
	v_mfma_f32_16x16x32_bf16 v[42:45], v[160:163], v[192:195], v[42:45]
	v_mfma_f32_16x16x32_bf16 v[34:37], v[152:155], v[200:203], v[34:37]
	v_mfma_f32_16x16x32_bf16 v[26:29], v[160:163], v[200:203], v[26:29]
	v_mfma_f32_16x16x32_bf16 v[18:21], v[152:155], v[208:211], v[18:21]
	v_mfma_f32_16x16x32_bf16 v[10:13], v[160:163], v[208:211], v[10:13]
	v_mfma_f32_16x16x32_bf16 v[62:65], v[156:159], v[188:191], v[62:65]
	v_mfma_f32_16x16x32_bf16 v[58:61], v[164:167], v[188:191], v[58:61]
	v_mfma_f32_16x16x32_bf16 v[50:53], v[156:159], v[196:199], v[50:53]
	v_mfma_f32_16x16x32_bf16 v[42:45], v[164:167], v[196:199], v[42:45]
	v_mfma_f32_16x16x32_bf16 v[34:37], v[156:159], v[204:207], v[34:37]
	v_mfma_f32_16x16x32_bf16 v[26:29], v[164:167], v[204:207], v[26:29]
	v_mfma_f32_16x16x32_bf16 v[18:21], v[156:159], v[212:215], v[18:21]
	v_mfma_f32_16x16x32_bf16 v[10:13], v[164:167], v[212:215], v[10:13]
	s_setprio 0
	s_setprio 1
	v_mfma_f32_16x16x32_bf16 v[54:57], v[168:171], v[184:187], v[54:57]
	v_mfma_f32_16x16x32_bf16 v[46:49], v[176:179], v[184:187], v[46:49]
	v_mfma_f32_16x16x32_bf16 v[38:41], v[168:171], v[192:195], v[38:41]
	v_mfma_f32_16x16x32_bf16 v[30:33], v[176:179], v[192:195], v[30:33]
	v_mfma_f32_16x16x32_bf16 v[22:25], v[168:171], v[200:203], v[22:25]
	v_mfma_f32_16x16x32_bf16 v[14:17], v[176:179], v[200:203], v[14:17]
	v_mfma_f32_16x16x32_bf16 v[6:9], v[168:171], v[208:211], v[6:9]
	v_mfma_f32_16x16x32_bf16 v[2:5], v[176:179], v[208:211], v[2:5]
	v_mfma_f32_16x16x32_bf16 v[54:57], v[172:175], v[188:191], v[54:57]
	v_mfma_f32_16x16x32_bf16 v[46:49], v[180:183], v[188:191], v[46:49]
	v_mfma_f32_16x16x32_bf16 v[38:41], v[172:175], v[196:199], v[38:41]
	v_mfma_f32_16x16x32_bf16 v[30:33], v[180:183], v[196:199], v[30:33]
	v_mfma_f32_16x16x32_bf16 v[22:25], v[172:175], v[204:207], v[22:25]
	v_mfma_f32_16x16x32_bf16 v[14:17], v[180:183], v[204:207], v[14:17]
	v_mfma_f32_16x16x32_bf16 v[6:9], v[172:175], v[212:215], v[6:9]
	v_mfma_f32_16x16x32_bf16 v[2:5], v[180:183], v[212:215], v[2:5]
	s_setprio 0
	s_barrier
	s_add_i32 s71, s71, 2
	s_add_u32 s30, s30, 0x100
	s_addc_u32 s31, s31, 0
	s_add_u32 s67, s67, 0x100
	s_addc_u32 s70, s70, 0
	s_cmp_gt_u32 s71, 61
	s_cbranch_scc0 .LBB0_387
	s_and_b64 vcc, exec, s[10:11]
	s_cbranch_vccz .LBB0_390
	s_barrier

.LBB0_1211:
	ds_read_b128 v[154:157], v150
	ds_read_b128 v[158:161], v150 offset:1024
	ds_read_b128 v[162:165], v150 offset:2048
	ds_read_b128 v[166:169], v150 offset:3072
	ds_read_b128 v[170:173], v151
	ds_read_b128 v[174:177], v151 offset:1024
	ds_read_b128 v[178:181], v151 offset:2048
	ds_read_b128 v[182:185], v151 offset:3072
	s_add_u32 s40, s36, 0xfff00080
	s_addc_u32 s41, s37, -1
	s_cmp_eq_u32 s64, 60
	s_cselect_b32 s43, s25, s41
	s_cselect_b32 s42, s60, s40
	s_cselect_b32 s41, s23, s63
	s_cselect_b32 s40, s61, s62
	v_lshl_add_u64 v[146:147], s[36:37], 0, v[138:139]
	s_add_i32 m0, s31, 0xc000
	ds_read_b128 v[186:189], v152
	ds_read_b128 v[190:193], v152 offset:1024
	ds_read_b128 v[194:197], v152 offset:2048
	ds_read_b128 v[198:201], v152 offset:3072
	ds_read_b128 v[202:205], v152 offset:4096
	ds_read_b128 v[206:209], v152 offset:5120
	ds_read_b128 v[210:213], v152 offset:6144
	ds_read_b128 v[214:217], v152 offset:7168
	global_load_lds_dwordx4 v[146:147], off
	v_lshl_add_u64 v[146:147], s[36:37], 0, v[140:141]
	s_add_i32 m0, s31, 0xe000
	s_nop 0
	global_load_lds_dwordx4 v[146:147], off
	s_waitcnt vmcnt(8)
	s_waitcnt lgkmcnt(0)
	s_setprio 1
	s_barrier
	v_mfma_f32_16x16x32_bf16 v[126:129], v[154:157], v[186:189], v[126:129]
	v_mfma_f32_16x16x32_bf16 v[122:125], v[162:165], v[186:189], v[122:125]
	v_mfma_f32_16x16x32_bf16 v[118:121], v[154:157], v[194:197], v[118:121]
	v_mfma_f32_16x16x32_bf16 v[110:113], v[162:165], v[194:197], v[110:113]
	v_mfma_f32_16x16x32_bf16 v[102:105], v[154:157], v[202:205], v[102:105]
	v_mfma_f32_16x16x32_bf16 v[94:97], v[162:165], v[202:205], v[94:97]
	v_mfma_f32_16x16x32_bf16 v[86:89], v[154:157], v[210:213], v[86:89]
	v_mfma_f32_16x16x32_bf16 v[78:81], v[162:165], v[210:213], v[78:81]
	v_mfma_f32_16x16x32_bf16 v[126:129], v[158:161], v[190:193], v[126:129]
	v_mfma_f32_16x16x32_bf16 v[122:125], v[166:169], v[190:193], v[122:125]
	v_mfma_f32_16x16x32_bf16 v[118:121], v[158:161], v[198:201], v[118:121]
	v_mfma_f32_16x16x32_bf16 v[110:113], v[166:169], v[198:201], v[110:113]
	v_mfma_f32_16x16x32_bf16 v[102:105], v[158:161], v[206:209], v[102:105]
	v_mfma_f32_16x16x32_bf16 v[94:97], v[166:169], v[206:209], v[94:97]
	v_mfma_f32_16x16x32_bf16 v[86:89], v[158:161], v[214:217], v[86:89]
	v_mfma_f32_16x16x32_bf16 v[78:81], v[166:169], v[214:217], v[78:81]
	s_setprio 0
	s_setprio 1
	v_mfma_f32_16x16x32_bf16 v[114:117], v[170:173], v[186:189], v[114:117]
	v_mfma_f32_16x16x32_bf16 v[106:109], v[178:181], v[186:189], v[106:109]
	v_mfma_f32_16x16x32_bf16 v[98:101], v[170:173], v[194:197], v[98:101]
	v_mfma_f32_16x16x32_bf16 v[90:93], v[178:181], v[194:197], v[90:93]
	v_mfma_f32_16x16x32_bf16 v[82:85], v[170:173], v[202:205], v[82:85]
	v_mfma_f32_16x16x32_bf16 v[74:77], v[178:181], v[202:205], v[74:77]
	v_mfma_f32_16x16x32_bf16 v[70:73], v[170:173], v[210:213], v[70:73]
	v_mfma_f32_16x16x32_bf16 v[66:69], v[178:181], v[210:213], v[66:69]
	v_mfma_f32_16x16x32_bf16 v[114:117], v[174:177], v[190:193], v[114:117]
	v_mfma_f32_16x16x32_bf16 v[106:109], v[182:185], v[190:193], v[106:109]
	v_mfma_f32_16x16x32_bf16 v[98:101], v[174:177], v[198:201], v[98:101]
	v_mfma_f32_16x16x32_bf16 v[90:93], v[182:185], v[198:201], v[90:93]
	v_mfma_f32_16x16x32_bf16 v[82:85], v[174:177], v[206:209], v[82:85]
	v_mfma_f32_16x16x32_bf16 v[74:77], v[182:185], v[206:209], v[74:77]
	v_mfma_f32_16x16x32_bf16 v[70:73], v[174:177], v[214:217], v[70:73]
	v_mfma_f32_16x16x32_bf16 v[66:69], v[182:185], v[214:217], v[66:69]
	s_setprio 0
	s_barrier
	s_add_i32 s65, s51, s15
	v_lshl_add_u64 v[146:147], s[40:41], 0, v[132:133]
	s_mov_b32 m0, s65
	ds_read_b128 v[186:189], v152 offset:16384
	ds_read_b128 v[190:193], v152 offset:17408
	ds_read_b128 v[194:197], v152 offset:18432
	ds_read_b128 v[198:201], v152 offset:19456
	ds_read_b128 v[202:205], v152 offset:20480
	ds_read_b128 v[206:209], v152 offset:21504
	ds_read_b128 v[210:213], v152 offset:22528
	ds_read_b128 v[214:217], v152 offset:23552
	global_load_lds_dwordx4 v[146:147], off
	s_add_i32 m0, s65, 0x2000
	s_add_u32 s66, s40, 0x100000
	v_lshl_add_u64 v[218:219], s[40:41], 0, v[136:137]
	s_addc_u32 s67, s41, 0
	s_add_i32 s65, s52, s15
	global_load_lds_dwordx4 v[218:219], off
	v_lshl_add_u64 v[220:221], s[66:67], 0, v[132:133]
	s_mov_b32 m0, s65
	v_lshl_add_u64 v[222:223], s[42:43], 0, v[134:135]
	global_load_lds_dwordx4 v[220:221], off
	v_lshl_add_u64 v[220:221], s[66:67], 0, v[136:137]
	s_add_i32 m0, s65, 0x2000
	s_nop 0
	global_load_lds_dwordx4 v[220:221], off
	v_lshl_add_u64 v[220:221], s[42:43], 0, v[130:131]
	s_mov_b32 m0, s31
	s_nop 0
	global_load_lds_dwordx4 v[220:221], off
	s_mov_b32 m0, s44
	s_nop 0
	global_load_lds_dwordx4 v[222:223], off
	s_waitcnt vmcnt(8)
	s_waitcnt lgkmcnt(0)
	s_setprio 1
	s_barrier
	v_mfma_f32_16x16x32_bf16 v[62:65], v[154:157], v[186:189], v[62:65]
	v_mfma_f32_16x16x32_bf16 v[58:61], v[162:165], v[186:189], v[58:61]
	v_mfma_f32_16x16x32_bf16 v[54:57], v[154:157], v[194:197], v[54:57]
	v_mfma_f32_16x16x32_bf16 v[46:49], v[162:165], v[194:197], v[46:49]
	v_mfma_f32_16x16x32_bf16 v[38:41], v[154:157], v[202:205], v[38:41]
	v_mfma_f32_16x16x32_bf16 v[30:33], v[162:165], v[202:205], v[30:33]
	v_mfma_f32_16x16x32_bf16 v[22:25], v[154:157], v[210:213], v[22:25]
	v_mfma_f32_16x16x32_bf16 v[14:17], v[162:165], v[210:213], v[14:17]
	v_mfma_f32_16x16x32_bf16 v[62:65], v[158:161], v[190:193], v[62:65]
	v_mfma_f32_16x16x32_bf16 v[58:61], v[166:169], v[190:193], v[58:61]
	v_mfma_f32_16x16x32_bf16 v[54:57], v[158:161], v[198:201], v[54:57]
	v_mfma_f32_16x16x32_bf16 v[46:49], v[166:169], v[198:201], v[46:49]
	v_mfma_f32_16x16x32_bf16 v[38:41], v[158:161], v[206:209], v[38:41]
	v_mfma_f32_16x16x32_bf16 v[30:33], v[166:169], v[206:209], v[30:33]
	v_mfma_f32_16x16x32_bf16 v[22:25], v[158:161], v[214:217], v[22:25]
	v_mfma_f32_16x16x32_bf16 v[14:17], v[166:169], v[214:217], v[14:17]
	s_setprio 0
	s_setprio 1
	v_mfma_f32_16x16x32_bf16 v[50:53], v[170:173], v[186:189], v[50:53]
	v_mfma_f32_16x16x32_bf16 v[42:45], v[178:181], v[186:189], v[42:45]
	v_mfma_f32_16x16x32_bf16 v[34:37], v[170:173], v[194:197], v[34:37]
	v_mfma_f32_16x16x32_bf16 v[26:29], v[178:181], v[194:197], v[26:29]
	v_mfma_f32_16x16x32_bf16 v[18:21], v[170:173], v[202:205], v[18:21]
	v_mfma_f32_16x16x32_bf16 v[10:13], v[178:181], v[202:205], v[10:13]
	v_mfma_f32_16x16x32_bf16 v[6:9], v[170:173], v[210:213], v[6:9]
	v_mfma_f32_16x16x32_bf16 v[2:5], v[178:181], v[210:213], v[2:5]
	v_mfma_f32_16x16x32_bf16 v[50:53], v[174:177], v[190:193], v[50:53]
	v_mfma_f32_16x16x32_bf16 v[42:45], v[182:185], v[190:193], v[42:45]
	v_mfma_f32_16x16x32_bf16 v[34:37], v[174:177], v[198:201], v[34:37]
	v_mfma_f32_16x16x32_bf16 v[26:29], v[182:185], v[198:201], v[26:29]
	v_mfma_f32_16x16x32_bf16 v[18:21], v[174:177], v[206:209], v[18:21]
	v_mfma_f32_16x16x32_bf16 v[10:13], v[182:185], v[206:209], v[10:13]
	v_mfma_f32_16x16x32_bf16 v[6:9], v[174:177], v[214:217], v[6:9]
	v_mfma_f32_16x16x32_bf16 v[2:5], v[182:185], v[214:217], v[2:5]
	s_setprio 0
	s_barrier
	s_add_i32 s65, 0, 0x18000
	v_add_u32_e32 v153, s65, v148
	s_add_i32 s66, 0, 0x1c000
	ds_read_b128 v[154:157], v153
	ds_read_b128 v[158:161], v153 offset:1024
	ds_read_b128 v[162:165], v153 offset:2048
	ds_read_b128 v[166:169], v153 offset:3072
	v_add_u32_e32 v153, s66, v148
	ds_read_b128 v[170:173], v153
	ds_read_b128 v[174:177], v153 offset:1024
	ds_read_b128 v[178:181], v153 offset:2048
	ds_read_b128 v[182:185], v153 offset:3072
	s_add_u32 s42, s42, 0x100000
	s_addc_u32 s43, s43, 0
	s_mov_b32 m0, s45
	v_lshl_add_u64 v[224:225], s[42:43], 0, v[130:131]
	ds_read_b128 v[186:189], v152 offset:32768
	ds_read_b128 v[190:193], v152 offset:33792
	ds_read_b128 v[194:197], v152 offset:34816
	ds_read_b128 v[198:201], v152 offset:35840
	ds_read_b128 v[202:205], v152 offset:36864
	ds_read_b128 v[206:209], v152 offset:37888
	ds_read_b128 v[210:213], v152 offset:38912
	ds_read_b128 v[214:217], v152 offset:39936
	global_load_lds_dwordx4 v[224:225], off
	v_lshl_add_u64 v[224:225], s[42:43], 0, v[134:135]
	s_mov_b32 m0, s46
	s_nop 0
	global_load_lds_dwordx4 v[224:225], off
	s_waitcnt vmcnt(8)
	s_waitcnt lgkmcnt(0)
	s_setprio 1
	s_barrier
	v_mfma_f32_16x16x32_bf16 v[126:129], v[154:157], v[186:189], v[126:129]
	v_mfma_f32_16x16x32_bf16 v[122:125], v[162:165], v[186:189], v[122:125]
	v_mfma_f32_16x16x32_bf16 v[118:121], v[154:157], v[194:197], v[118:121]
	v_mfma_f32_16x16x32_bf16 v[110:113], v[162:165], v[194:197], v[110:113]
	v_mfma_f32_16x16x32_bf16 v[102:105], v[154:157], v[202:205], v[102:105]
	v_mfma_f32_16x16x32_bf16 v[94:97], v[162:165], v[202:205], v[94:97]
	v_mfma_f32_16x16x32_bf16 v[86:89], v[154:157], v[210:213], v[86:89]
	v_mfma_f32_16x16x32_bf16 v[78:81], v[162:165], v[210:213], v[78:81]
	v_mfma_f32_16x16x32_bf16 v[126:129], v[158:161], v[190:193], v[126:129]
	v_mfma_f32_16x16x32_bf16 v[122:125], v[166:169], v[190:193], v[122:125]
	v_mfma_f32_16x16x32_bf16 v[118:121], v[158:161], v[198:201], v[118:121]
	v_mfma_f32_16x16x32_bf16 v[110:113], v[166:169], v[198:201], v[110:113]
	v_mfma_f32_16x16x32_bf16 v[102:105], v[158:161], v[206:209], v[102:105]
	v_mfma_f32_16x16x32_bf16 v[94:97], v[166:169], v[206:209], v[94:97]
	v_mfma_f32_16x16x32_bf16 v[86:89], v[158:161], v[214:217], v[86:89]
	v_mfma_f32_16x16x32_bf16 v[78:81], v[166:169], v[214:217], v[78:81]
	s_setprio 0
	s_setprio 1
	v_mfma_f32_16x16x32_bf16 v[114:117], v[170:173], v[186:189], v[114:117]
	v_mfma_f32_16x16x32_bf16 v[106:109], v[178:181], v[186:189], v[106:109]
	v_mfma_f32_16x16x32_bf16 v[98:101], v[170:173], v[194:197], v[98:101]
	v_mfma_f32_16x16x32_bf16 v[90:93], v[178:181], v[194:197], v[90:93]
	v_mfma_f32_16x16x32_bf16 v[82:85], v[170:173], v[202:205], v[82:85]
	v_mfma_f32_16x16x32_bf16 v[74:77], v[178:181], v[202:205], v[74:77]
	v_mfma_f32_16x16x32_bf16 v[70:73], v[170:173], v[210:213], v[70:73]
	v_mfma_f32_16x16x32_bf16 v[66:69], v[178:181], v[210:213], v[66:69]
	v_mfma_f32_16x16x32_bf16 v[114:117], v[174:177], v[190:193], v[114:117]
	v_mfma_f32_16x16x32_bf16 v[106:109], v[182:185], v[190:193], v[106:109]
	v_mfma_f32_16x16x32_bf16 v[98:101], v[174:177], v[198:201], v[98:101]
	v_mfma_f32_16x16x32_bf16 v[90:93], v[182:185], v[198:201], v[90:93]
	v_mfma_f32_16x16x32_bf16 v[82:85], v[174:177], v[206:209], v[82:85]
	v_mfma_f32_16x16x32_bf16 v[74:77], v[182:185], v[206:209], v[74:77]
	v_mfma_f32_16x16x32_bf16 v[70:73], v[174:177], v[214:217], v[70:73]
	v_mfma_f32_16x16x32_bf16 v[66:69], v[182:185], v[214:217], v[66:69]
	s_setprio 0
	s_barrier
	s_add_i32 s42, s65, s15
	v_lshl_add_u64 v[146:147], v[146:147], 0, s[10:11]
	s_mov_b32 m0, s42
	ds_read_b128 v[186:189], v152 offset:49152
	ds_read_b128 v[190:193], v152 offset:50176
	ds_read_b128 v[194:197], v152 offset:51200
	ds_read_b128 v[198:201], v152 offset:52224
	ds_read_b128 v[202:205], v152 offset:53248
	ds_read_b128 v[206:209], v152 offset:54272
	ds_read_b128 v[210:213], v152 offset:55296
	ds_read_b128 v[214:217], v152 offset:56320
	global_load_lds_dwordx4 v[146:147], off
	s_add_i32 m0, s42, 0x2000
	s_add_u32 s40, s40, 0x100080
	v_lshl_add_u64 v[146:147], v[218:219], 0, s[10:11]
	s_addc_u32 s41, s41, 0
	s_add_i32 s42, s66, s15
	global_load_lds_dwordx4 v[146:147], off
	v_lshl_add_u64 v[146:147], s[40:41], 0, v[132:133]
	s_mov_b32 m0, s42
	s_nop 0
	global_load_lds_dwordx4 v[146:147], off
	v_lshl_add_u64 v[146:147], s[40:41], 0, v[136:137]
	s_add_i32 m0, s42, 0x2000
	s_nop 0
	global_load_lds_dwordx4 v[146:147], off
	v_lshl_add_u64 v[146:147], v[220:221], 0, s[10:11]
	s_mov_b32 m0, s48
	s_nop 0
	global_load_lds_dwordx4 v[146:147], off
	v_lshl_add_u64 v[146:147], v[222:223], 0, s[10:11]
	s_mov_b32 m0, s49
	s_nop 0
	global_load_lds_dwordx4 v[146:147], off
	s_waitcnt vmcnt(8)
	s_waitcnt lgkmcnt(0)
	s_setprio 1
	s_barrier
	v_mfma_f32_16x16x32_bf16 v[62:65], v[154:157], v[186:189], v[62:65]
	v_mfma_f32_16x16x32_bf16 v[58:61], v[162:165], v[186:189], v[58:61]
	v_mfma_f32_16x16x32_bf16 v[54:57], v[154:157], v[194:197], v[54:57]
	v_mfma_f32_16x16x32_bf16 v[46:49], v[162:165], v[194:197], v[46:49]
	v_mfma_f32_16x16x32_bf16 v[38:41], v[154:157], v[202:205], v[38:41]
	v_mfma_f32_16x16x32_bf16 v[30:33], v[162:165], v[202:205], v[30:33]
	v_mfma_f32_16x16x32_bf16 v[22:25], v[154:157], v[210:213], v[22:25]
	v_mfma_f32_16x16x32_bf16 v[14:17], v[162:165], v[210:213], v[14:17]
	v_mfma_f32_16x16x32_bf16 v[62:65], v[158:161], v[190:193], v[62:65]
	v_mfma_f32_16x16x32_bf16 v[58:61], v[166:169], v[190:193], v[58:61]
	v_mfma_f32_16x16x32_bf16 v[54:57], v[158:161], v[198:201], v[54:57]
	v_mfma_f32_16x16x32_bf16 v[46:49], v[166:169], v[198:201], v[46:49]
	v_mfma_f32_16x16x32_bf16 v[38:41], v[158:161], v[206:209], v[38:41]
	v_mfma_f32_16x16x32_bf16 v[30:33], v[166:169], v[206:209], v[30:33]
	v_mfma_f32_16x16x32_bf16 v[22:25], v[158:161], v[214:217], v[22:25]
	v_mfma_f32_16x16x32_bf16 v[14:17], v[166:169], v[214:217], v[14:17]
	s_setprio 0
	s_setprio 1
	v_mfma_f32_16x16x32_bf16 v[50:53], v[170:173], v[186:189], v[50:53]
	v_mfma_f32_16x16x32_bf16 v[42:45], v[178:181], v[186:189], v[42:45]
	v_mfma_f32_16x16x32_bf16 v[34:37], v[170:173], v[194:197], v[34:37]
	v_mfma_f32_16x16x32_bf16 v[26:29], v[178:181], v[194:197], v[26:29]
	v_mfma_f32_16x16x32_bf16 v[18:21], v[170:173], v[202:205], v[18:21]
	v_mfma_f32_16x16x32_bf16 v[10:13], v[178:181], v[202:205], v[10:13]
	v_mfma_f32_16x16x32_bf16 v[6:9], v[170:173], v[210:213], v[6:9]
	v_mfma_f32_16x16x32_bf16 v[2:5], v[178:181], v[210:213], v[2:5]
	v_mfma_f32_16x16x32_bf16 v[50:53], v[174:177], v[190:193], v[50:53]
	v_mfma_f32_16x16x32_bf16 v[42:45], v[182:185], v[190:193], v[42:45]
	v_mfma_f32_16x16x32_bf16 v[34:37], v[174:177], v[198:201], v[34:37]
	v_mfma_f32_16x16x32_bf16 v[26:29], v[182:185], v[198:201], v[26:29]
	v_mfma_f32_16x16x32_bf16 v[18:21], v[174:177], v[206:209], v[18:21]
	v_mfma_f32_16x16x32_bf16 v[10:13], v[182:185], v[206:209], v[10:13]
	v_mfma_f32_16x16x32_bf16 v[6:9], v[174:177], v[214:217], v[6:9]
	v_mfma_f32_16x16x32_bf16 v[2:5], v[182:185], v[214:217], v[2:5]
	s_setprio 0
	s_barrier
	s_add_i32 s64, s64, 2
	s_add_u32 s36, s36, 0x100
	s_addc_u32 s37, s37, 0
	s_add_u32 s62, s62, 0x100
	s_addc_u32 s63, s63, 0
	s_cmp_gt_u32 s64, 61
	s_cbranch_scc0 .LBB0_1211
	s_and_b64 vcc, exec, s[12:13]
	s_cbranch_vccz .LBB0_1214
	s_barrier

.LBB0_1337:
	ds_read_b128 v[154:157], v151
	ds_read_b128 v[158:161], v151 offset:1024
	ds_read_b128 v[162:165], v151 offset:2048
	ds_read_b128 v[166:169], v151 offset:3072
	ds_read_b128 v[170:173], v152
	ds_read_b128 v[174:177], v152 offset:1024
	ds_read_b128 v[178:181], v152 offset:2048
	ds_read_b128 v[182:185], v152 offset:3072
	s_add_u32 s26, s24, 0xfff00080
	s_addc_u32 s27, s25, -1
	s_cmp_eq_u32 s53, 60
	s_cselect_b32 s29, s17, s27
	s_cselect_b32 s28, s49, s26
	s_cselect_b32 s27, s13, s52
	s_cselect_b32 s26, s50, s51
	v_lshl_add_u64 v[146:147], s[24:25], 0, v[138:139]
	s_add_i32 m0, s23, 0xc000
	ds_read_b128 v[186:189], v153
	ds_read_b128 v[190:193], v153 offset:1024
	ds_read_b128 v[194:197], v153 offset:2048
	ds_read_b128 v[198:201], v153 offset:3072
	ds_read_b128 v[202:205], v153 offset:4096
	ds_read_b128 v[206:209], v153 offset:5120
	ds_read_b128 v[210:213], v153 offset:6144
	ds_read_b128 v[214:217], v153 offset:7168
	global_load_lds_dwordx4 v[146:147], off
	v_lshl_add_u64 v[146:147], s[24:25], 0, v[140:141]
	s_add_i32 m0, s23, 0xe000
	s_nop 0
	global_load_lds_dwordx4 v[146:147], off
	s_waitcnt vmcnt(8)
	s_waitcnt lgkmcnt(0)
	s_setprio 1
	s_barrier
	v_mfma_f32_16x16x32_bf16 v[126:129], v[154:157], v[186:189], v[126:129]
	v_mfma_f32_16x16x32_bf16 v[122:125], v[162:165], v[186:189], v[122:125]
	v_mfma_f32_16x16x32_bf16 v[110:113], v[154:157], v[194:197], v[110:113]
	v_mfma_f32_16x16x32_bf16 v[106:109], v[162:165], v[194:197], v[106:109]
	v_mfma_f32_16x16x32_bf16 v[94:97], v[154:157], v[202:205], v[94:97]
	v_mfma_f32_16x16x32_bf16 v[90:93], v[162:165], v[202:205], v[90:93]
	v_mfma_f32_16x16x32_bf16 v[78:81], v[154:157], v[210:213], v[78:81]
	v_mfma_f32_16x16x32_bf16 v[74:77], v[162:165], v[210:213], v[74:77]
	v_mfma_f32_16x16x32_bf16 v[126:129], v[158:161], v[190:193], v[126:129]
	v_mfma_f32_16x16x32_bf16 v[122:125], v[166:169], v[190:193], v[122:125]
	v_mfma_f32_16x16x32_bf16 v[110:113], v[158:161], v[198:201], v[110:113]
	v_mfma_f32_16x16x32_bf16 v[106:109], v[166:169], v[198:201], v[106:109]
	v_mfma_f32_16x16x32_bf16 v[94:97], v[158:161], v[206:209], v[94:97]
	v_mfma_f32_16x16x32_bf16 v[90:93], v[166:169], v[206:209], v[90:93]
	v_mfma_f32_16x16x32_bf16 v[78:81], v[158:161], v[214:217], v[78:81]
	v_mfma_f32_16x16x32_bf16 v[74:77], v[166:169], v[214:217], v[74:77]
	s_setprio 0
	s_setprio 1
	v_mfma_f32_16x16x32_bf16 v[118:121], v[170:173], v[186:189], v[118:121]
	v_mfma_f32_16x16x32_bf16 v[114:117], v[178:181], v[186:189], v[114:117]
	v_mfma_f32_16x16x32_bf16 v[102:105], v[170:173], v[194:197], v[102:105]
	v_mfma_f32_16x16x32_bf16 v[98:101], v[178:181], v[194:197], v[98:101]
	v_mfma_f32_16x16x32_bf16 v[86:89], v[170:173], v[202:205], v[86:89]
	v_mfma_f32_16x16x32_bf16 v[82:85], v[178:181], v[202:205], v[82:85]
	v_mfma_f32_16x16x32_bf16 v[70:73], v[170:173], v[210:213], v[70:73]
	v_mfma_f32_16x16x32_bf16 v[66:69], v[178:181], v[210:213], v[66:69]
	v_mfma_f32_16x16x32_bf16 v[118:121], v[174:177], v[190:193], v[118:121]
	v_mfma_f32_16x16x32_bf16 v[114:117], v[182:185], v[190:193], v[114:117]
	v_mfma_f32_16x16x32_bf16 v[102:105], v[174:177], v[198:201], v[102:105]
	v_mfma_f32_16x16x32_bf16 v[98:101], v[182:185], v[198:201], v[98:101]
	v_mfma_f32_16x16x32_bf16 v[86:89], v[174:177], v[206:209], v[86:89]
	v_mfma_f32_16x16x32_bf16 v[82:85], v[182:185], v[206:209], v[82:85]
	v_mfma_f32_16x16x32_bf16 v[70:73], v[174:177], v[214:217], v[70:73]
	v_mfma_f32_16x16x32_bf16 v[66:69], v[182:185], v[214:217], v[66:69]
	s_setprio 0
	s_barrier
	s_add_i32 s54, s45, s15
	v_lshl_add_u64 v[146:147], s[26:27], 0, v[134:135]
	s_mov_b32 m0, s54
	ds_read_b128 v[186:189], v153 offset:16384
	ds_read_b128 v[190:193], v153 offset:17408
	ds_read_b128 v[194:197], v153 offset:18432
	ds_read_b128 v[198:201], v153 offset:19456
	ds_read_b128 v[202:205], v153 offset:20480
	ds_read_b128 v[206:209], v153 offset:21504
	ds_read_b128 v[210:213], v153 offset:22528
	ds_read_b128 v[214:217], v153 offset:23552
	global_load_lds_dwordx4 v[146:147], off
	s_add_i32 m0, s54, 0x2000
	s_add_u32 s54, s26, 0x100000
	v_lshl_add_u64 v[218:219], s[26:27], 0, v[130:131]
	s_addc_u32 s55, s27, 0
	s_add_i32 s56, s46, s15
	global_load_lds_dwordx4 v[218:219], off
	v_lshl_add_u64 v[220:221], s[54:55], 0, v[134:135]
	s_mov_b32 m0, s56
	v_lshl_add_u64 v[222:223], s[28:29], 0, v[132:133]
	global_load_lds_dwordx4 v[220:221], off
	v_lshl_add_u64 v[220:221], s[54:55], 0, v[130:131]
	s_add_i32 m0, s56, 0x2000
	s_nop 0
	global_load_lds_dwordx4 v[220:221], off
	v_lshl_add_u64 v[220:221], s[28:29], 0, v[136:137]
	s_mov_b32 m0, s23
	s_nop 0
	global_load_lds_dwordx4 v[220:221], off
	s_mov_b32 m0, s36
	s_nop 0
	global_load_lds_dwordx4 v[222:223], off
	s_waitcnt vmcnt(8)
	s_waitcnt lgkmcnt(0)
	s_setprio 1
	s_barrier
	v_mfma_f32_16x16x32_bf16 v[62:65], v[154:157], v[186:189], v[62:65]
	v_mfma_f32_16x16x32_bf16 v[58:61], v[162:165], v[186:189], v[58:61]
	v_mfma_f32_16x16x32_bf16 v[46:49], v[154:157], v[194:197], v[46:49]
	v_mfma_f32_16x16x32_bf16 v[42:45], v[162:165], v[194:197], v[42:45]
	v_mfma_f32_16x16x32_bf16 v[30:33], v[154:157], v[202:205], v[30:33]
	v_mfma_f32_16x16x32_bf16 v[26:29], v[162:165], v[202:205], v[26:29]
	v_mfma_f32_16x16x32_bf16 v[14:17], v[154:157], v[210:213], v[14:17]
	v_mfma_f32_16x16x32_bf16 v[10:13], v[162:165], v[210:213], v[10:13]
	v_mfma_f32_16x16x32_bf16 v[62:65], v[158:161], v[190:193], v[62:65]
	v_mfma_f32_16x16x32_bf16 v[58:61], v[166:169], v[190:193], v[58:61]
	v_mfma_f32_16x16x32_bf16 v[46:49], v[158:161], v[198:201], v[46:49]
	v_mfma_f32_16x16x32_bf16 v[42:45], v[166:169], v[198:201], v[42:45]
	v_mfma_f32_16x16x32_bf16 v[30:33], v[158:161], v[206:209], v[30:33]
	v_mfma_f32_16x16x32_bf16 v[26:29], v[166:169], v[206:209], v[26:29]
	v_mfma_f32_16x16x32_bf16 v[14:17], v[158:161], v[214:217], v[14:17]
	v_mfma_f32_16x16x32_bf16 v[10:13], v[166:169], v[214:217], v[10:13]
	s_setprio 0
	s_setprio 1
	v_mfma_f32_16x16x32_bf16 v[54:57], v[170:173], v[186:189], v[54:57]
	v_mfma_f32_16x16x32_bf16 v[50:53], v[178:181], v[186:189], v[50:53]
	v_mfma_f32_16x16x32_bf16 v[38:41], v[170:173], v[194:197], v[38:41]
	v_mfma_f32_16x16x32_bf16 v[34:37], v[178:181], v[194:197], v[34:37]
	v_mfma_f32_16x16x32_bf16 v[22:25], v[170:173], v[202:205], v[22:25]
	v_mfma_f32_16x16x32_bf16 v[18:21], v[178:181], v[202:205], v[18:21]
	v_mfma_f32_16x16x32_bf16 v[6:9], v[170:173], v[210:213], v[6:9]
	v_mfma_f32_16x16x32_bf16 v[2:5], v[178:181], v[210:213], v[2:5]
	v_mfma_f32_16x16x32_bf16 v[54:57], v[174:177], v[190:193], v[54:57]
	v_mfma_f32_16x16x32_bf16 v[50:53], v[182:185], v[190:193], v[50:53]
	v_mfma_f32_16x16x32_bf16 v[38:41], v[174:177], v[198:201], v[38:41]
	v_mfma_f32_16x16x32_bf16 v[34:37], v[182:185], v[198:201], v[34:37]
	v_mfma_f32_16x16x32_bf16 v[22:25], v[174:177], v[206:209], v[22:25]
	v_mfma_f32_16x16x32_bf16 v[18:21], v[182:185], v[206:209], v[18:21]
	v_mfma_f32_16x16x32_bf16 v[6:9], v[174:177], v[214:217], v[6:9]
	v_mfma_f32_16x16x32_bf16 v[2:5], v[182:185], v[214:217], v[2:5]
	s_setprio 0
	s_barrier
	s_add_i32 s54, 0, 0x18000
	s_add_i32 s55, 0, 0x1c000
	v_add_u32_e32 v166, s54, v149
	v_add_u32_e32 v182, s55, v149
	ds_read_b128 v[154:157], v166
	ds_read_b128 v[158:161], v166 offset:1024
	ds_read_b128 v[162:165], v166 offset:2048
	ds_read_b128 v[166:169], v166 offset:3072
	ds_read_b128 v[170:173], v182
	ds_read_b128 v[174:177], v182 offset:1024
	ds_read_b128 v[178:181], v182 offset:2048
	ds_read_b128 v[182:185], v182 offset:3072
	s_add_u32 s28, s28, 0x100000
	s_addc_u32 s29, s29, 0
	s_mov_b32 m0, s37
	v_lshl_add_u64 v[224:225], s[28:29], 0, v[136:137]
	ds_read_b128 v[186:189], v153 offset:32768
	ds_read_b128 v[190:193], v153 offset:33792
	ds_read_b128 v[194:197], v153 offset:34816
	ds_read_b128 v[198:201], v153 offset:35840
	ds_read_b128 v[202:205], v153 offset:36864
	ds_read_b128 v[206:209], v153 offset:37888
	ds_read_b128 v[210:213], v153 offset:38912
	ds_read_b128 v[214:217], v153 offset:39936
	global_load_lds_dwordx4 v[224:225], off
	v_lshl_add_u64 v[224:225], s[28:29], 0, v[132:133]
	s_mov_b32 m0, s40
	s_nop 0
	global_load_lds_dwordx4 v[224:225], off
	s_waitcnt vmcnt(8)
	s_waitcnt lgkmcnt(0)
	s_setprio 1
	s_barrier
	v_mfma_f32_16x16x32_bf16 v[126:129], v[154:157], v[186:189], v[126:129]
	v_mfma_f32_16x16x32_bf16 v[122:125], v[162:165], v[186:189], v[122:125]
	v_mfma_f32_16x16x32_bf16 v[110:113], v[154:157], v[194:197], v[110:113]
	v_mfma_f32_16x16x32_bf16 v[106:109], v[162:165], v[194:197], v[106:109]
	v_mfma_f32_16x16x32_bf16 v[94:97], v[154:157], v[202:205], v[94:97]
	v_mfma_f32_16x16x32_bf16 v[90:93], v[162:165], v[202:205], v[90:93]
	v_mfma_f32_16x16x32_bf16 v[78:81], v[154:157], v[210:213], v[78:81]
	v_mfma_f32_16x16x32_bf16 v[74:77], v[162:165], v[210:213], v[74:77]
	v_mfma_f32_16x16x32_bf16 v[126:129], v[158:161], v[190:193], v[126:129]
	v_mfma_f32_16x16x32_bf16 v[122:125], v[166:169], v[190:193], v[122:125]
	v_mfma_f32_16x16x32_bf16 v[110:113], v[158:161], v[198:201], v[110:113]
	v_mfma_f32_16x16x32_bf16 v[106:109], v[166:169], v[198:201], v[106:109]
	v_mfma_f32_16x16x32_bf16 v[94:97], v[158:161], v[206:209], v[94:97]
	v_mfma_f32_16x16x32_bf16 v[90:93], v[166:169], v[206:209], v[90:93]
	v_mfma_f32_16x16x32_bf16 v[78:81], v[158:161], v[214:217], v[78:81]
	v_mfma_f32_16x16x32_bf16 v[74:77], v[166:169], v[214:217], v[74:77]
	s_setprio 0
	s_setprio 1
	v_mfma_f32_16x16x32_bf16 v[118:121], v[170:173], v[186:189], v[118:121]
	v_mfma_f32_16x16x32_bf16 v[114:117], v[178:181], v[186:189], v[114:117]
	v_mfma_f32_16x16x32_bf16 v[102:105], v[170:173], v[194:197], v[102:105]
	v_mfma_f32_16x16x32_bf16 v[98:101], v[178:181], v[194:197], v[98:101]
	v_mfma_f32_16x16x32_bf16 v[86:89], v[170:173], v[202:205], v[86:89]
	v_mfma_f32_16x16x32_bf16 v[82:85], v[178:181], v[202:205], v[82:85]
	v_mfma_f32_16x16x32_bf16 v[70:73], v[170:173], v[210:213], v[70:73]
	v_mfma_f32_16x16x32_bf16 v[66:69], v[178:181], v[210:213], v[66:69]
	v_mfma_f32_16x16x32_bf16 v[118:121], v[174:177], v[190:193], v[118:121]
	v_mfma_f32_16x16x32_bf16 v[114:117], v[182:185], v[190:193], v[114:117]
	v_mfma_f32_16x16x32_bf16 v[102:105], v[174:177], v[198:201], v[102:105]
	v_mfma_f32_16x16x32_bf16 v[98:101], v[182:185], v[198:201], v[98:101]
	v_mfma_f32_16x16x32_bf16 v[86:89], v[174:177], v[206:209], v[86:89]
	v_mfma_f32_16x16x32_bf16 v[82:85], v[182:185], v[206:209], v[82:85]
	v_mfma_f32_16x16x32_bf16 v[70:73], v[174:177], v[214:217], v[70:73]
	v_mfma_f32_16x16x32_bf16 v[66:69], v[182:185], v[214:217], v[66:69]
	s_setprio 0
	s_barrier
	s_add_i32 s28, s54, s15
	v_lshl_add_u64 v[146:147], v[146:147], 0, s[8:9]
	s_mov_b32 m0, s28
	ds_read_b128 v[186:189], v153 offset:49152
	ds_read_b128 v[190:193], v153 offset:50176
	ds_read_b128 v[194:197], v153 offset:51200
	ds_read_b128 v[198:201], v153 offset:52224
	ds_read_b128 v[202:205], v153 offset:53248
	ds_read_b128 v[206:209], v153 offset:54272
	ds_read_b128 v[210:213], v153 offset:55296
	ds_read_b128 v[214:217], v153 offset:56320
	global_load_lds_dwordx4 v[146:147], off
	s_add_i32 m0, s28, 0x2000
	s_add_u32 s26, s26, 0x100080
	v_lshl_add_u64 v[146:147], v[218:219], 0, s[8:9]
	s_addc_u32 s27, s27, 0
	s_add_i32 s28, s55, s15
	global_load_lds_dwordx4 v[146:147], off
	v_lshl_add_u64 v[146:147], s[26:27], 0, v[134:135]
	s_mov_b32 m0, s28
	s_nop 0
	global_load_lds_dwordx4 v[146:147], off
	v_lshl_add_u64 v[146:147], s[26:27], 0, v[130:131]
	s_add_i32 m0, s28, 0x2000
	s_nop 0
	global_load_lds_dwordx4 v[146:147], off
	v_lshl_add_u64 v[146:147], v[220:221], 0, s[8:9]
	s_mov_b32 m0, s42
	s_nop 0
	global_load_lds_dwordx4 v[146:147], off
	v_lshl_add_u64 v[146:147], v[222:223], 0, s[8:9]
	s_mov_b32 m0, s43
	s_nop 0
	global_load_lds_dwordx4 v[146:147], off
	s_waitcnt vmcnt(8)
	s_waitcnt lgkmcnt(0)
	s_setprio 1
	s_barrier
	v_mfma_f32_16x16x32_bf16 v[62:65], v[154:157], v[186:189], v[62:65]
	v_mfma_f32_16x16x32_bf16 v[58:61], v[162:165], v[186:189], v[58:61]
	v_mfma_f32_16x16x32_bf16 v[46:49], v[154:157], v[194:197], v[46:49]
	v_mfma_f32_16x16x32_bf16 v[42:45], v[162:165], v[194:197], v[42:45]
	v_mfma_f32_16x16x32_bf16 v[30:33], v[154:157], v[202:205], v[30:33]
	v_mfma_f32_16x16x32_bf16 v[26:29], v[162:165], v[202:205], v[26:29]
	v_mfma_f32_16x16x32_bf16 v[14:17], v[154:157], v[210:213], v[14:17]
	v_mfma_f32_16x16x32_bf16 v[10:13], v[162:165], v[210:213], v[10:13]
	v_mfma_f32_16x16x32_bf16 v[62:65], v[158:161], v[190:193], v[62:65]
	v_mfma_f32_16x16x32_bf16 v[58:61], v[166:169], v[190:193], v[58:61]
	v_mfma_f32_16x16x32_bf16 v[46:49], v[158:161], v[198:201], v[46:49]
	v_mfma_f32_16x16x32_bf16 v[42:45], v[166:169], v[198:201], v[42:45]
	v_mfma_f32_16x16x32_bf16 v[30:33], v[158:161], v[206:209], v[30:33]
	v_mfma_f32_16x16x32_bf16 v[26:29], v[166:169], v[206:209], v[26:29]
	v_mfma_f32_16x16x32_bf16 v[14:17], v[158:161], v[214:217], v[14:17]
	v_mfma_f32_16x16x32_bf16 v[10:13], v[166:169], v[214:217], v[10:13]
	s_setprio 0
	s_setprio 1
	v_mfma_f32_16x16x32_bf16 v[54:57], v[170:173], v[186:189], v[54:57]
	v_mfma_f32_16x16x32_bf16 v[50:53], v[178:181], v[186:189], v[50:53]
	v_mfma_f32_16x16x32_bf16 v[38:41], v[170:173], v[194:197], v[38:41]
	v_mfma_f32_16x16x32_bf16 v[34:37], v[178:181], v[194:197], v[34:37]
	v_mfma_f32_16x16x32_bf16 v[22:25], v[170:173], v[202:205], v[22:25]
	v_mfma_f32_16x16x32_bf16 v[18:21], v[178:181], v[202:205], v[18:21]
	v_mfma_f32_16x16x32_bf16 v[6:9], v[170:173], v[210:213], v[6:9]
	v_mfma_f32_16x16x32_bf16 v[2:5], v[178:181], v[210:213], v[2:5]
	v_mfma_f32_16x16x32_bf16 v[54:57], v[174:177], v[190:193], v[54:57]
	v_mfma_f32_16x16x32_bf16 v[50:53], v[182:185], v[190:193], v[50:53]
	v_mfma_f32_16x16x32_bf16 v[38:41], v[174:177], v[198:201], v[38:41]
	v_mfma_f32_16x16x32_bf16 v[34:37], v[182:185], v[198:201], v[34:37]
	v_mfma_f32_16x16x32_bf16 v[22:25], v[174:177], v[206:209], v[22:25]
	v_mfma_f32_16x16x32_bf16 v[18:21], v[182:185], v[206:209], v[18:21]
	v_mfma_f32_16x16x32_bf16 v[6:9], v[174:177], v[214:217], v[6:9]
	v_mfma_f32_16x16x32_bf16 v[2:5], v[182:185], v[214:217], v[2:5]
	s_setprio 0
	s_barrier
	s_add_i32 s53, s53, 2
	s_add_u32 s24, s24, 0x100
	s_addc_u32 s25, s25, 0
	s_add_u32 s51, s51, 0x100
	s_addc_u32 s52, s52, 0
	s_cmp_gt_u32 s53, 61
	s_cbranch_scc0 .LBB0_1337
	s_and_b64 vcc, exec, s[10:11]
	s_cbranch_vccz .LBB0_1340
	s_barrier

.LBB0_1434:
	ds_read_b128 v[154:157], v150
	ds_read_b128 v[158:161], v150 offset:1024
	ds_read_b128 v[162:165], v150 offset:2048
	ds_read_b128 v[166:169], v150 offset:3072
	ds_read_b128 v[170:173], v151
	ds_read_b128 v[174:177], v151 offset:1024
	ds_read_b128 v[178:181], v151 offset:2048
	ds_read_b128 v[182:185], v151 offset:3072
	s_add_u32 s30, s28, 0x100
	s_addc_u32 s31, s29, 0
	s_cmpk_eq_i32 s66, 0xa8
	s_cselect_b32 s41, s5, s31
	s_cselect_b32 s40, s4, s30
	s_cselect_b32 s37, s27, s65
	s_cselect_b32 s36, s26, s64
	v_lshl_add_u64 v[146:147], s[28:29], 0, v[138:139]
	s_add_i32 m0, s15, 0xc000
	ds_read_b128 v[186:189], v152
	ds_read_b128 v[190:193], v152 offset:1024
	ds_read_b128 v[194:197], v152 offset:2048
	ds_read_b128 v[198:201], v152 offset:3072
	ds_read_b128 v[202:205], v152 offset:4096
	ds_read_b128 v[206:209], v152 offset:5120
	ds_read_b128 v[210:213], v152 offset:6144
	ds_read_b128 v[214:217], v152 offset:7168
	global_load_lds_dwordx4 v[146:147], off
	v_lshl_add_u64 v[146:147], s[28:29], 0, v[140:141]
	s_add_i32 m0, s15, 0xe000
	s_nop 0
	global_load_lds_dwordx4 v[146:147], off
	s_waitcnt vmcnt(8)
	s_waitcnt lgkmcnt(0)
	s_setprio 1
	s_barrier
	v_mfma_f32_16x16x32_bf16 v[126:129], v[154:157], v[186:189], v[126:129]
	v_mfma_f32_16x16x32_bf16 v[122:125], v[162:165], v[186:189], v[122:125]
	v_mfma_f32_16x16x32_bf16 v[118:121], v[154:157], v[194:197], v[118:121]
	v_mfma_f32_16x16x32_bf16 v[110:113], v[162:165], v[194:197], v[110:113]
	v_mfma_f32_16x16x32_bf16 v[102:105], v[154:157], v[202:205], v[102:105]
	v_mfma_f32_16x16x32_bf16 v[94:97], v[162:165], v[202:205], v[94:97]
	v_mfma_f32_16x16x32_bf16 v[86:89], v[154:157], v[210:213], v[86:89]
	v_mfma_f32_16x16x32_bf16 v[78:81], v[162:165], v[210:213], v[78:81]
	v_mfma_f32_16x16x32_bf16 v[126:129], v[158:161], v[190:193], v[126:129]
	v_mfma_f32_16x16x32_bf16 v[122:125], v[166:169], v[190:193], v[122:125]
	v_mfma_f32_16x16x32_bf16 v[118:121], v[158:161], v[198:201], v[118:121]
	v_mfma_f32_16x16x32_bf16 v[110:113], v[166:169], v[198:201], v[110:113]
	v_mfma_f32_16x16x32_bf16 v[102:105], v[158:161], v[206:209], v[102:105]
	v_mfma_f32_16x16x32_bf16 v[94:97], v[166:169], v[206:209], v[94:97]
	v_mfma_f32_16x16x32_bf16 v[86:89], v[158:161], v[214:217], v[86:89]
	v_mfma_f32_16x16x32_bf16 v[78:81], v[166:169], v[214:217], v[78:81]
	s_setprio 0
	s_setprio 1
	v_mfma_f32_16x16x32_bf16 v[114:117], v[170:173], v[186:189], v[114:117]
	v_mfma_f32_16x16x32_bf16 v[106:109], v[178:181], v[186:189], v[106:109]
	v_mfma_f32_16x16x32_bf16 v[98:101], v[170:173], v[194:197], v[98:101]
	v_mfma_f32_16x16x32_bf16 v[90:93], v[178:181], v[194:197], v[90:93]
	v_mfma_f32_16x16x32_bf16 v[82:85], v[170:173], v[202:205], v[82:85]
	v_mfma_f32_16x16x32_bf16 v[74:77], v[178:181], v[202:205], v[74:77]
	v_mfma_f32_16x16x32_bf16 v[70:73], v[170:173], v[210:213], v[70:73]
	v_mfma_f32_16x16x32_bf16 v[66:69], v[178:181], v[210:213], v[66:69]
	v_mfma_f32_16x16x32_bf16 v[114:117], v[174:177], v[190:193], v[114:117]
	v_mfma_f32_16x16x32_bf16 v[106:109], v[182:185], v[190:193], v[106:109]
	v_mfma_f32_16x16x32_bf16 v[98:101], v[174:177], v[198:201], v[98:101]
	v_mfma_f32_16x16x32_bf16 v[90:93], v[182:185], v[198:201], v[90:93]
	v_mfma_f32_16x16x32_bf16 v[82:85], v[174:177], v[206:209], v[82:85]
	v_mfma_f32_16x16x32_bf16 v[74:77], v[182:185], v[206:209], v[74:77]
	v_mfma_f32_16x16x32_bf16 v[70:73], v[174:177], v[214:217], v[70:73]
	v_mfma_f32_16x16x32_bf16 v[66:69], v[182:185], v[214:217], v[66:69]
	s_setprio 0
	s_barrier
	s_add_i32 s28, s52, s3
	v_lshl_add_u64 v[146:147], s[36:37], 0, v[132:133]
	s_mov_b32 m0, s28
	ds_read_b128 v[186:189], v152 offset:16384
	ds_read_b128 v[190:193], v152 offset:17408
	ds_read_b128 v[194:197], v152 offset:18432
	ds_read_b128 v[198:201], v152 offset:19456
	ds_read_b128 v[202:205], v152 offset:20480
	ds_read_b128 v[206:209], v152 offset:21504
	ds_read_b128 v[210:213], v152 offset:22528
	ds_read_b128 v[214:217], v152 offset:23552
	global_load_lds_dwordx4 v[146:147], off
	s_add_i32 m0, s28, 0x2000
	s_add_u32 s28, s36, 0x2b0000
	v_lshl_add_u64 v[218:219], s[36:37], 0, v[136:137]
	s_addc_u32 s29, s37, 0
	s_add_i32 s67, s53, s3
	global_load_lds_dwordx4 v[218:219], off
	v_lshl_add_u64 v[220:221], s[28:29], 0, v[132:133]
	s_mov_b32 m0, s67
	v_lshl_add_u64 v[222:223], s[40:41], 0, v[134:135]
	global_load_lds_dwordx4 v[220:221], off
	v_lshl_add_u64 v[220:221], s[28:29], 0, v[136:137]
	s_add_i32 m0, s67, 0x2000
	s_nop 0
	global_load_lds_dwordx4 v[220:221], off
	v_lshl_add_u64 v[220:221], s[40:41], 0, v[130:131]
	s_mov_b32 m0, s15
	s_nop 0
	global_load_lds_dwordx4 v[220:221], off
	s_mov_b32 m0, s42
	s_nop 0
	global_load_lds_dwordx4 v[222:223], off
	s_waitcnt vmcnt(8)
	s_waitcnt lgkmcnt(0)
	s_setprio 1
	s_barrier
	v_mfma_f32_16x16x32_bf16 v[62:65], v[154:157], v[186:189], v[62:65]
	v_mfma_f32_16x16x32_bf16 v[58:61], v[162:165], v[186:189], v[58:61]
	v_mfma_f32_16x16x32_bf16 v[54:57], v[154:157], v[194:197], v[54:57]
	v_mfma_f32_16x16x32_bf16 v[46:49], v[162:165], v[194:197], v[46:49]
	v_mfma_f32_16x16x32_bf16 v[38:41], v[154:157], v[202:205], v[38:41]
	v_mfma_f32_16x16x32_bf16 v[30:33], v[162:165], v[202:205], v[30:33]
	v_mfma_f32_16x16x32_bf16 v[22:25], v[154:157], v[210:213], v[22:25]
	v_mfma_f32_16x16x32_bf16 v[14:17], v[162:165], v[210:213], v[14:17]
	v_mfma_f32_16x16x32_bf16 v[62:65], v[158:161], v[190:193], v[62:65]
	v_mfma_f32_16x16x32_bf16 v[58:61], v[166:169], v[190:193], v[58:61]
	v_mfma_f32_16x16x32_bf16 v[54:57], v[158:161], v[198:201], v[54:57]
	v_mfma_f32_16x16x32_bf16 v[46:49], v[166:169], v[198:201], v[46:49]
	v_mfma_f32_16x16x32_bf16 v[38:41], v[158:161], v[206:209], v[38:41]
	v_mfma_f32_16x16x32_bf16 v[30:33], v[166:169], v[206:209], v[30:33]
	v_mfma_f32_16x16x32_bf16 v[22:25], v[158:161], v[214:217], v[22:25]
	v_mfma_f32_16x16x32_bf16 v[14:17], v[166:169], v[214:217], v[14:17]
	s_setprio 0
	s_setprio 1
	v_mfma_f32_16x16x32_bf16 v[50:53], v[170:173], v[186:189], v[50:53]
	v_mfma_f32_16x16x32_bf16 v[42:45], v[178:181], v[186:189], v[42:45]
	v_mfma_f32_16x16x32_bf16 v[34:37], v[170:173], v[194:197], v[34:37]
	v_mfma_f32_16x16x32_bf16 v[26:29], v[178:181], v[194:197], v[26:29]
	v_mfma_f32_16x16x32_bf16 v[18:21], v[170:173], v[202:205], v[18:21]
	v_mfma_f32_16x16x32_bf16 v[10:13], v[178:181], v[202:205], v[10:13]
	v_mfma_f32_16x16x32_bf16 v[6:9], v[170:173], v[210:213], v[6:9]
	v_mfma_f32_16x16x32_bf16 v[2:5], v[178:181], v[210:213], v[2:5]
	v_mfma_f32_16x16x32_bf16 v[50:53], v[174:177], v[190:193], v[50:53]
	v_mfma_f32_16x16x32_bf16 v[42:45], v[182:185], v[190:193], v[42:45]
	v_mfma_f32_16x16x32_bf16 v[34:37], v[174:177], v[198:201], v[34:37]
	v_mfma_f32_16x16x32_bf16 v[26:29], v[182:185], v[198:201], v[26:29]
	v_mfma_f32_16x16x32_bf16 v[18:21], v[174:177], v[206:209], v[18:21]
	v_mfma_f32_16x16x32_bf16 v[10:13], v[182:185], v[206:209], v[10:13]
	v_mfma_f32_16x16x32_bf16 v[6:9], v[174:177], v[214:217], v[6:9]
	v_mfma_f32_16x16x32_bf16 v[2:5], v[182:185], v[214:217], v[2:5]
	s_setprio 0
	s_barrier
	s_add_i32 s67, 0, 0x18000
	v_add_u32_e32 v153, s67, v148
	s_add_i32 s68, 0, 0x1c000
	ds_read_b128 v[154:157], v153
	ds_read_b128 v[158:161], v153 offset:1024
	ds_read_b128 v[162:165], v153 offset:2048
	ds_read_b128 v[166:169], v153 offset:3072
	v_add_u32_e32 v153, s68, v148
	ds_read_b128 v[170:173], v153
	ds_read_b128 v[174:177], v153 offset:1024
	ds_read_b128 v[178:181], v153 offset:2048
	ds_read_b128 v[182:185], v153 offset:3072
	s_add_u32 s28, s40, 0x2b0000
	s_addc_u32 s29, s41, 0
	s_mov_b32 m0, s43
	v_lshl_add_u64 v[224:225], s[28:29], 0, v[130:131]
	ds_read_b128 v[186:189], v152 offset:32768
	ds_read_b128 v[190:193], v152 offset:33792
	ds_read_b128 v[194:197], v152 offset:34816
	ds_read_b128 v[198:201], v152 offset:35840
	ds_read_b128 v[202:205], v152 offset:36864
	ds_read_b128 v[206:209], v152 offset:37888
	ds_read_b128 v[210:213], v152 offset:38912
	ds_read_b128 v[214:217], v152 offset:39936
	global_load_lds_dwordx4 v[224:225], off
	v_lshl_add_u64 v[224:225], s[28:29], 0, v[134:135]
	s_mov_b32 m0, s44
	s_nop 0
	global_load_lds_dwordx4 v[224:225], off
	s_waitcnt vmcnt(8)
	s_waitcnt lgkmcnt(0)
	s_setprio 1
	s_barrier
	v_mfma_f32_16x16x32_bf16 v[126:129], v[154:157], v[186:189], v[126:129]
	v_mfma_f32_16x16x32_bf16 v[122:125], v[162:165], v[186:189], v[122:125]
	v_mfma_f32_16x16x32_bf16 v[118:121], v[154:157], v[194:197], v[118:121]
	v_mfma_f32_16x16x32_bf16 v[110:113], v[162:165], v[194:197], v[110:113]
	v_mfma_f32_16x16x32_bf16 v[102:105], v[154:157], v[202:205], v[102:105]
	v_mfma_f32_16x16x32_bf16 v[94:97], v[162:165], v[202:205], v[94:97]
	v_mfma_f32_16x16x32_bf16 v[86:89], v[154:157], v[210:213], v[86:89]
	v_mfma_f32_16x16x32_bf16 v[78:81], v[162:165], v[210:213], v[78:81]
	v_mfma_f32_16x16x32_bf16 v[126:129], v[158:161], v[190:193], v[126:129]
	v_mfma_f32_16x16x32_bf16 v[122:125], v[166:169], v[190:193], v[122:125]
	v_mfma_f32_16x16x32_bf16 v[118:121], v[158:161], v[198:201], v[118:121]
	v_mfma_f32_16x16x32_bf16 v[110:113], v[166:169], v[198:201], v[110:113]
	v_mfma_f32_16x16x32_bf16 v[102:105], v[158:161], v[206:209], v[102:105]
	v_mfma_f32_16x16x32_bf16 v[94:97], v[166:169], v[206:209], v[94:97]
	v_mfma_f32_16x16x32_bf16 v[86:89], v[158:161], v[214:217], v[86:89]
	v_mfma_f32_16x16x32_bf16 v[78:81], v[166:169], v[214:217], v[78:81]
	s_setprio 0
	s_setprio 1
	v_mfma_f32_16x16x32_bf16 v[114:117], v[170:173], v[186:189], v[114:117]
	v_mfma_f32_16x16x32_bf16 v[106:109], v[178:181], v[186:189], v[106:109]
	v_mfma_f32_16x16x32_bf16 v[98:101], v[170:173], v[194:197], v[98:101]
	v_mfma_f32_16x16x32_bf16 v[90:93], v[178:181], v[194:197], v[90:93]
	v_mfma_f32_16x16x32_bf16 v[82:85], v[170:173], v[202:205], v[82:85]
	v_mfma_f32_16x16x32_bf16 v[74:77], v[178:181], v[202:205], v[74:77]
	v_mfma_f32_16x16x32_bf16 v[70:73], v[170:173], v[210:213], v[70:73]
	v_mfma_f32_16x16x32_bf16 v[66:69], v[178:181], v[210:213], v[66:69]
	v_mfma_f32_16x16x32_bf16 v[114:117], v[174:177], v[190:193], v[114:117]
	v_mfma_f32_16x16x32_bf16 v[106:109], v[182:185], v[190:193], v[106:109]
	v_mfma_f32_16x16x32_bf16 v[98:101], v[174:177], v[198:201], v[98:101]
	v_mfma_f32_16x16x32_bf16 v[90:93], v[182:185], v[198:201], v[90:93]
	v_mfma_f32_16x16x32_bf16 v[82:85], v[174:177], v[206:209], v[82:85]
	v_mfma_f32_16x16x32_bf16 v[74:77], v[182:185], v[206:209], v[74:77]
	v_mfma_f32_16x16x32_bf16 v[70:73], v[174:177], v[214:217], v[70:73]
	v_mfma_f32_16x16x32_bf16 v[66:69], v[182:185], v[214:217], v[66:69]
	s_setprio 0
	s_barrier
	s_add_i32 s28, s67, s3
	v_lshl_add_u64 v[146:147], v[146:147], 0, s[12:13]
	s_mov_b32 m0, s28
	ds_read_b128 v[186:189], v152 offset:49152
	ds_read_b128 v[190:193], v152 offset:50176
	ds_read_b128 v[194:197], v152 offset:51200
	ds_read_b128 v[198:201], v152 offset:52224
	ds_read_b128 v[202:205], v152 offset:53248
	ds_read_b128 v[206:209], v152 offset:54272
	ds_read_b128 v[210:213], v152 offset:55296
	ds_read_b128 v[214:217], v152 offset:56320
	global_load_lds_dwordx4 v[146:147], off
	s_add_i32 m0, s28, 0x2000
	s_add_u32 s28, s36, 0x2b0080
	v_lshl_add_u64 v[146:147], v[218:219], 0, s[12:13]
	s_addc_u32 s29, s37, 0
	s_add_i32 s36, s68, s3
	global_load_lds_dwordx4 v[146:147], off
	v_lshl_add_u64 v[146:147], s[28:29], 0, v[132:133]
	s_mov_b32 m0, s36
	s_nop 0
	global_load_lds_dwordx4 v[146:147], off
	v_lshl_add_u64 v[146:147], s[28:29], 0, v[136:137]
	s_add_i32 m0, s36, 0x2000
	s_nop 0
	global_load_lds_dwordx4 v[146:147], off
	v_lshl_add_u64 v[146:147], v[220:221], 0, s[12:13]
	s_mov_b32 m0, s46
	s_nop 0
	global_load_lds_dwordx4 v[146:147], off
	v_lshl_add_u64 v[146:147], v[222:223], 0, s[12:13]
	s_mov_b32 m0, s47
	s_nop 0
	global_load_lds_dwordx4 v[146:147], off
	s_waitcnt vmcnt(8)
	s_waitcnt lgkmcnt(0)
	s_setprio 1
	s_barrier
	v_mfma_f32_16x16x32_bf16 v[62:65], v[154:157], v[186:189], v[62:65]
	v_mfma_f32_16x16x32_bf16 v[58:61], v[162:165], v[186:189], v[58:61]
	v_mfma_f32_16x16x32_bf16 v[54:57], v[154:157], v[194:197], v[54:57]
	v_mfma_f32_16x16x32_bf16 v[46:49], v[162:165], v[194:197], v[46:49]
	v_mfma_f32_16x16x32_bf16 v[38:41], v[154:157], v[202:205], v[38:41]
	v_mfma_f32_16x16x32_bf16 v[30:33], v[162:165], v[202:205], v[30:33]
	v_mfma_f32_16x16x32_bf16 v[22:25], v[154:157], v[210:213], v[22:25]
	v_mfma_f32_16x16x32_bf16 v[14:17], v[162:165], v[210:213], v[14:17]
	v_mfma_f32_16x16x32_bf16 v[62:65], v[158:161], v[190:193], v[62:65]
	v_mfma_f32_16x16x32_bf16 v[58:61], v[166:169], v[190:193], v[58:61]
	v_mfma_f32_16x16x32_bf16 v[54:57], v[158:161], v[198:201], v[54:57]
	v_mfma_f32_16x16x32_bf16 v[46:49], v[166:169], v[198:201], v[46:49]
	v_mfma_f32_16x16x32_bf16 v[38:41], v[158:161], v[206:209], v[38:41]
	v_mfma_f32_16x16x32_bf16 v[30:33], v[166:169], v[206:209], v[30:33]
	v_mfma_f32_16x16x32_bf16 v[22:25], v[158:161], v[214:217], v[22:25]
	v_mfma_f32_16x16x32_bf16 v[14:17], v[166:169], v[214:217], v[14:17]
	s_setprio 0
	s_setprio 1
	v_mfma_f32_16x16x32_bf16 v[50:53], v[170:173], v[186:189], v[50:53]
	v_mfma_f32_16x16x32_bf16 v[42:45], v[178:181], v[186:189], v[42:45]
	v_mfma_f32_16x16x32_bf16 v[34:37], v[170:173], v[194:197], v[34:37]
	v_mfma_f32_16x16x32_bf16 v[26:29], v[178:181], v[194:197], v[26:29]
	v_mfma_f32_16x16x32_bf16 v[18:21], v[170:173], v[202:205], v[18:21]
	v_mfma_f32_16x16x32_bf16 v[10:13], v[178:181], v[202:205], v[10:13]
	v_mfma_f32_16x16x32_bf16 v[6:9], v[170:173], v[210:213], v[6:9]
	v_mfma_f32_16x16x32_bf16 v[2:5], v[178:181], v[210:213], v[2:5]
	v_mfma_f32_16x16x32_bf16 v[50:53], v[174:177], v[190:193], v[50:53]
	v_mfma_f32_16x16x32_bf16 v[42:45], v[182:185], v[190:193], v[42:45]
	v_mfma_f32_16x16x32_bf16 v[34:37], v[174:177], v[198:201], v[34:37]
	v_mfma_f32_16x16x32_bf16 v[26:29], v[182:185], v[198:201], v[26:29]
	v_mfma_f32_16x16x32_bf16 v[18:21], v[174:177], v[206:209], v[18:21]
	v_mfma_f32_16x16x32_bf16 v[10:13], v[182:185], v[206:209], v[10:13]
	v_mfma_f32_16x16x32_bf16 v[6:9], v[174:177], v[214:217], v[6:9]
	v_mfma_f32_16x16x32_bf16 v[2:5], v[182:185], v[214:217], v[2:5]
	s_setprio 0
	s_barrier
	s_add_i32 s66, s66, 2
	s_add_u32 s64, s64, 0x100
	s_addc_u32 s65, s65, 0
	s_cmpk_gt_u32 s66, 0xa9
	s_mov_b64 s[28:29], s[30:31]
	s_cbranch_scc0 .LBB0_1434
	s_and_b64 vcc, exec, s[16:17]
	s_cbranch_vccz .LBB0_1437
	s_barrier
